# P8 row pass unrolled x4 and software-pipelined one iteration deep (second register bank for odd iterations)
# baseline (speedup 1.0000x reference)
.LBB0_1396:
	v_lshl_add_u64 v[98:99], s[82:83], 0, v[158:159]
	v_add_co_u32_e32 v86, vcc, 0x7400000, v98
	v_lshl_add_u64 v[100:101], s[82:83], 0, v[156:157]
	s_nop 0
	v_addc_co_u32_e32 v87, vcc, 0, v99, vcc
	s_mov_b64 s[64:65], 0x7000000
	v_add_co_u32_e32 v90, vcc, 0x7000000, v100
	v_lshl_add_u64 v[88:89], v[100:101], 0, s[64:65]
	s_nop 0
	v_addc_co_u32_e32 v91, vcc, 0, v101, vcc
	s_mov_b32 s3, 0x7410000
	global_load_dwordx4 v[82:85], v[88:89], off offset:48
	global_load_dwordx4 v[94:97], v[88:89], off offset:32
	global_load_dword v179, v[86:87], off
	global_load_dwordx4 v[110:113], v[88:89], off offset:16
	v_add_co_u32_e32 v86, vcc, s3, v98
	s_mov_b32 s3, 0x7100000
	s_nop 0
	v_addc_co_u32_e32 v87, vcc, 0, v99, vcc
	global_load_dwordx4 v[126:129], v[90:91], off
	global_load_dword v196, v[86:87], off
	v_add_co_u32_e32 v86, vcc, s3, v100
	s_mov_b32 s3, 0x7420000
	s_nop 0
	v_addc_co_u32_e32 v87, vcc, 0, v101, vcc
	v_add_co_u32_e32 v114, vcc, s3, v98
	s_mov_b32 s3, 0x7200000
	s_nop 0
	v_addc_co_u32_e32 v115, vcc, 0, v99, vcc
	v_add_co_u32_e32 v184, vcc, s3, v100
	s_mov_b64 s[64:65], 0x7100000
	s_nop 0
	v_addc_co_u32_e32 v185, vcc, 0, v101, vcc
	s_mov_b32 s3, 0x7430000
	v_lshl_add_u64 v[90:91], v[100:101], 0, s[64:65]
	s_mov_b64 s[64:65], 0x7200000
	v_add_co_u32_e32 v98, vcc, s3, v98
	v_lshl_add_u64 v[116:117], v[100:101], 0, s[64:65]
	s_nop 0
	v_addc_co_u32_e32 v99, vcc, 0, v99, vcc
	s_mov_b32 s3, 0x7300000
	global_load_dwordx4 v[180:183], v[86:87], off
	s_nop 0
	global_load_dwordx4 v[86:89], v[90:91], off offset:48
	global_load_dwordx4 v[102:105], v[90:91], off offset:32
	global_load_dwordx4 v[118:121], v[90:91], off offset:16
	s_nop 0
	global_load_dwordx4 v[90:93], v[116:117], off offset:48
	global_load_dwordx4 v[106:109], v[116:117], off offset:32
	global_load_dword v197, v[114:115], off
	global_load_dwordx4 v[122:125], v[116:117], off offset:16
	s_nop 0
	global_load_dwordx4 v[184:187], v[184:185], off
	s_nop 0
	global_load_dword v198, v[98:99], off
	s_mov_b64 s[64:65], 0x7300000
	v_add_co_u32_e32 v98, vcc, s3, v100
	v_lshl_add_u64 v[192:193], v[100:101], 0, s[64:65]
	s_nop 0
	v_addc_co_u32_e32 v99, vcc, 0, v101, vcc
	global_load_dwordx4 v[188:191], v[98:99], off
	s_nop 0
	global_load_dwordx4 v[98:101], v[192:193], off offset:48
	global_load_dwordx4 v[114:117], v[192:193], off offset:32
	s_nop 0
	global_load_dwordx4 v[192:195], v[192:193], off offset:16
	v_lshl_add_u64 v[158:159], v[158:159], 0, s[96:97]
	v_lshl_add_u64 v[156:157], v[156:157], 0, s[14:15]
	v_lshl_add_u64 v[18:19], s[82:83], 0, v[158:159]
	v_add_co_u32_e32 v6, vcc, 0x7400000, v18
	v_lshl_add_u64 v[20:21], s[82:83], 0, v[156:157]
	s_nop 0
	v_addc_co_u32_e32 v7, vcc, 0, v19, vcc
	s_mov_b64 s[64:65], 0x7000000
	v_add_co_u32_e32 v10, vcc, 0x7000000, v20
	v_lshl_add_u64 v[8:9], v[20:21], 0, s[64:65]
	s_nop 0
	v_addc_co_u32_e32 v11, vcc, 0, v21, vcc
	s_mov_b32 s3, 0x7410000
	global_load_dwordx4 v[2:5], v[8:9], off offset:48
	global_load_dwordx4 v[14:17], v[8:9], off offset:32
	global_load_dword v201, v[6:7], off
	global_load_dwordx4 v[30:33], v[8:9], off offset:16
	v_add_co_u32_e32 v6, vcc, s3, v18
	s_mov_b32 s3, 0x7100000
	s_nop 0
	v_addc_co_u32_e32 v7, vcc, 0, v19, vcc
	global_load_dwordx4 v[46:49], v[10:11], off
	global_load_dword v218, v[6:7], off
	v_add_co_u32_e32 v6, vcc, s3, v20
	s_mov_b32 s3, 0x7420000
	s_nop 0
	v_addc_co_u32_e32 v7, vcc, 0, v21, vcc
	v_add_co_u32_e32 v34, vcc, s3, v18
	s_mov_b32 s3, 0x7200000
	s_nop 0
	v_addc_co_u32_e32 v35, vcc, 0, v19, vcc
	v_add_co_u32_e32 v206, vcc, s3, v20
	s_mov_b64 s[64:65], 0x7100000
	s_nop 0
	v_addc_co_u32_e32 v207, vcc, 0, v21, vcc
	s_mov_b32 s3, 0x7430000
	v_lshl_add_u64 v[10:11], v[20:21], 0, s[64:65]
	s_mov_b64 s[64:65], 0x7200000
	v_add_co_u32_e32 v18, vcc, s3, v18
	v_lshl_add_u64 v[36:37], v[20:21], 0, s[64:65]
	s_nop 0
	v_addc_co_u32_e32 v19, vcc, 0, v19, vcc
	s_mov_b32 s3, 0x7300000
	global_load_dwordx4 v[202:205], v[6:7], off
	s_nop 0
	global_load_dwordx4 v[6:9], v[10:11], off offset:48
	global_load_dwordx4 v[22:25], v[10:11], off offset:32
	global_load_dwordx4 v[38:41], v[10:11], off offset:16
	s_nop 0
	global_load_dwordx4 v[10:13], v[36:37], off offset:48
	global_load_dwordx4 v[26:29], v[36:37], off offset:32
	global_load_dword v219, v[34:35], off
	global_load_dwordx4 v[42:45], v[36:37], off offset:16
	s_nop 0
	global_load_dwordx4 v[206:209], v[206:207], off
	s_nop 0
	global_load_dword v220, v[18:19], off
	s_mov_b64 s[64:65], 0x7300000
	v_add_co_u32_e32 v18, vcc, s3, v20
	v_lshl_add_u64 v[214:215], v[20:21], 0, s[64:65]
	s_nop 0
	v_addc_co_u32_e32 v19, vcc, 0, v21, vcc
	global_load_dwordx4 v[210:213], v[18:19], off
	s_nop 0
	global_load_dwordx4 v[18:21], v[214:215], off offset:48
	global_load_dwordx4 v[34:37], v[214:215], off offset:32
	s_nop 0
	global_load_dwordx4 v[214:217], v[214:215], off offset:16
	v_lshl_add_u64 v[158:159], v[158:159], 0, s[96:97]
	v_lshl_add_u64 v[156:157], v[156:157], 0, s[14:15]
	s_waitcnt vmcnt(34)
	v_add_f32_e32 v179, v179, v196
	s_waitcnt vmcnt(24)
	v_add_f32_e32 v196, v197, v198
	v_add_f32_e32 v179, v179, v196
	v_fmamk_f32 v179, v179, 0x3a800000, v166
	s_mov_b32 s3, 0xf800000
	v_cmp_gt_f32_e32 vcc, s3, v179
	v_mul_f32_e32 v196, 0x4f800000, v179
	v_add_f32_e32 v126, v126, v180
	v_cndmask_b32_e32 v179, v179, v196, vcc
	v_sqrt_f32_e32 v196, v179
	s_waitcnt vmcnt(23)
	v_add_f32_e32 v180, v184, v188
	v_add_f32_e32 v126, v126, v180
	v_add_f32_e32 v127, v127, v181
	v_add_u32_e32 v197, -1, v196
	v_fma_f32 v198, -v197, v196, v179
	v_cmp_ge_f32_e64 s[64:65], 0, v198
	v_add_u32_e32 v198, 1, v196
	v_add_f32_e32 v180, v185, v189
	v_cndmask_b32_e64 v197, v196, v197, s[64:65]
	v_fma_f32 v196, -v198, v196, v179
	v_cmp_lt_f32_e64 s[64:65], 0, v196
	v_add_f32_e32 v82, v82, v86
	s_waitcnt vmcnt(22)
	v_add_f32_e32 v86, v90, v98
	v_cndmask_b32_e64 v196, v197, v198, s[64:65]
	v_mul_f32_e32 v197, 0x37800000, v196
	v_cndmask_b32_e32 v196, v196, v197, vcc
	v_cmp_class_f32_e32 vcc, v179, v168
	v_add_f32_e32 v127, v127, v180
	v_add_f32_e32 v128, v128, v182
	v_cndmask_b32_e32 v179, v196, v179, vcc
	v_div_scale_f32 v196, s[64:65], v179, v179, 1.0
	v_rcp_f32_e32 v197, v196
	v_add_f32_e32 v180, v186, v190
	v_add_f32_e32 v110, v110, v118
	s_waitcnt vmcnt(20)
	v_add_f32_e32 v118, v122, v192
	v_fma_f32 v198, -v196, v197, 1.0
	v_fmac_f32_e32 v197, v198, v197
	v_div_scale_f32 v198, vcc, 1.0, v179, 1.0
	v_mul_f32_e32 v199, v198, v197
	v_fma_f32 v200, -v196, v199, v198
	v_fmac_f32_e32 v199, v200, v197
	v_fma_f32 v196, -v196, v199, v198
	v_div_fmas_f32 v196, v196, v197, v199
	v_add_f32_e32 v82, v82, v86
	v_add_f32_e32 v83, v83, v87
	v_add_f32_e32 v86, v91, v99
	v_div_fixup_f32 v179, v196, v179, 1.0
	v_add_f32_e32 v128, v128, v180
	v_add_f32_e32 v129, v129, v183
	v_add_f32_e32 v180, v187, v191
	v_add_f32_e32 v110, v110, v118
	v_add_f32_e32 v111, v111, v119
	v_add_f32_e32 v118, v123, v193
	v_add_f32_e32 v83, v83, v86
	v_add_f32_e32 v84, v84, v88
	v_add_f32_e32 v86, v92, v100
	v_fma_f32 v126, v126, v179, v66
	v_fma_f32 v127, v127, v179, v67
	v_add_f32_e32 v129, v129, v180
	v_add_f32_e32 v111, v111, v118
	v_add_f32_e32 v112, v112, v120
	v_add_f32_e32 v118, v124, v194
	v_add_f32_e32 v94, v94, v102
	v_add_f32_e32 v102, v106, v114
	v_add_f32_e32 v84, v84, v86
	v_add_f32_e32 v85, v85, v89
	v_add_f32_e32 v86, v93, v101
	v_fma_f32 v128, v128, v179, v68
	v_fma_f32 v129, v129, v179, v69
	v_add_f32_e32 v112, v112, v118
	v_add_f32_e32 v113, v113, v121
	v_add_f32_e32 v118, v125, v195
	v_add_f32_e32 v94, v94, v102
	v_add_f32_e32 v95, v95, v103
	v_add_f32_e32 v102, v107, v115
	v_add_f32_e32 v85, v85, v86
	v_max_f32_e32 v86, v126, v127
	v_fma_f32 v110, v110, v179, v70
	v_fma_f32 v111, v111, v179, v71
	v_add_f32_e32 v113, v113, v118
	v_add_f32_e32 v95, v95, v102
	v_add_f32_e32 v96, v96, v104
	v_add_f32_e32 v102, v108, v116
	v_max3_f32 v86, v86, v128, v129
	v_fma_f32 v112, v112, v179, v72
	v_fma_f32 v113, v113, v179, v73
	v_add_f32_e32 v96, v96, v102
	v_add_f32_e32 v97, v97, v105
	v_add_f32_e32 v102, v109, v117
	v_max3_f32 v86, v86, v110, v111
	v_fma_f32 v94, v179, v94, v74
	v_fma_f32 v95, v179, v95, v75
	v_add_f32_e32 v97, v97, v102
	v_max3_f32 v86, v86, v112, v113
	v_fma_f32 v96, v179, v96, v76
	v_fma_f32 v97, v179, v97, v77
	v_max3_f32 v86, v86, v94, v95
	v_fma_f32 v82, v179, v82, v78
	v_fma_f32 v83, v179, v83, v79
	v_max3_f32 v86, v86, v96, v97
	v_fma_f32 v84, v179, v84, v80
	v_fma_f32 v85, v179, v85, v81
	v_max3_f32 v86, v86, v82, v83
	v_max3_f32 v86, v86, v84, v85
	v_sub_f32_e32 v87, v126, v86
	v_mul_f32_e32 v88, 0x3fb8aa3b, v87
	v_fma_f32 v89, v87, s1, -v88
	v_rndne_f32_e32 v90, v88
	v_fmac_f32_e32 v89, 0x32a5705f, v87
	v_sub_f32_e32 v88, v88, v90
	v_add_f32_e32 v88, v88, v89
	v_exp_f32_e32 v88, v88
	v_cvt_i32_f32_e32 v89, v90
	v_cmp_ngt_f32_e32 vcc, s6, v87
	v_sub_f32_e32 v82, v82, v86
	v_sub_f32_e32 v83, v83, v86
	v_ldexp_f32 v88, v88, v89
	v_sub_f32_e32 v89, v127, v86
	v_mul_f32_e32 v90, 0x3fb8aa3b, v89
	v_fma_f32 v91, v89, s1, -v90
	v_rndne_f32_e32 v92, v90
	v_fmac_f32_e32 v91, 0x32a5705f, v89
	v_sub_f32_e32 v90, v90, v92
	v_add_f32_e32 v90, v90, v91
	v_exp_f32_e32 v90, v90
	v_cvt_i32_f32_e32 v91, v92
	v_cndmask_b32_e32 v88, 0, v88, vcc
	v_cmp_nlt_f32_e32 vcc, s7, v87
	s_movk_i32 s3, 0x5ff
	v_ldexp_f32 v90, v90, v91
	v_cndmask_b32_e32 v87, v173, v88, vcc
	v_cmp_ngt_f32_e32 vcc, s6, v89
	v_cndmask_b32_e64 v88, 0, v87, s[30:31]
	v_cndmask_b32_e32 v90, 0, v90, vcc
	v_cmp_nlt_f32_e32 vcc, s7, v89
	s_nop 0
	v_cndmask_b32_e32 v89, v173, v90, vcc
	v_add_f32_e32 v87, v87, v89
	v_cndmask_b32_e64 v88, v88, v89, s[34:35]
	v_sub_f32_e32 v89, v128, v86
	v_mul_f32_e32 v90, 0x3fb8aa3b, v89
	v_fma_f32 v91, v89, s1, -v90
	v_rndne_f32_e32 v92, v90
	v_fmac_f32_e32 v91, 0x32a5705f, v89
	v_sub_f32_e32 v90, v90, v92
	v_add_f32_e32 v90, v90, v91
	v_exp_f32_e32 v90, v90
	v_cvt_i32_f32_e32 v91, v92
	v_cmp_ngt_f32_e32 vcc, s6, v89
	v_ldexp_f32 v90, v90, v91
	s_nop 0
	v_cndmask_b32_e32 v90, 0, v90, vcc
	v_cmp_nlt_f32_e32 vcc, s7, v89
	s_nop 1
	v_cndmask_b32_e32 v89, v173, v90, vcc
	v_add_f32_e32 v87, v89, v87
	v_cndmask_b32_e64 v88, v88, v89, s[36:37]
	v_sub_f32_e32 v89, v129, v86
	v_mul_f32_e32 v90, 0x3fb8aa3b, v89
	v_fma_f32 v91, v89, s1, -v90
	v_rndne_f32_e32 v92, v90
	v_fmac_f32_e32 v91, 0x32a5705f, v89
	v_sub_f32_e32 v90, v90, v92
	v_add_f32_e32 v90, v90, v91
	v_exp_f32_e32 v90, v90
	v_cvt_i32_f32_e32 v91, v92
	v_cmp_ngt_f32_e32 vcc, s6, v89
	v_ldexp_f32 v90, v90, v91
	s_nop 0
	v_cndmask_b32_e32 v90, 0, v90, vcc
	v_cmp_nlt_f32_e32 vcc, s7, v89
	s_nop 1
	v_cndmask_b32_e32 v89, v173, v90, vcc
	v_add_f32_e32 v87, v89, v87
	v_cndmask_b32_e64 v88, v88, v89, s[38:39]
	v_sub_f32_e32 v89, v110, v86
	v_mul_f32_e32 v90, 0x3fb8aa3b, v89
	v_fma_f32 v91, v89, s1, -v90
	v_rndne_f32_e32 v92, v90
	v_fmac_f32_e32 v91, 0x32a5705f, v89
	v_sub_f32_e32 v90, v90, v92
	v_add_f32_e32 v90, v90, v91
	v_exp_f32_e32 v90, v90
	v_cvt_i32_f32_e32 v91, v92
	v_cmp_ngt_f32_e32 vcc, s6, v89
	v_ldexp_f32 v90, v90, v91
	s_nop 0
	v_cndmask_b32_e32 v90, 0, v90, vcc
	v_cmp_nlt_f32_e32 vcc, s7, v89
	s_nop 1
	v_cndmask_b32_e32 v89, v173, v90, vcc
	v_add_f32_e32 v87, v89, v87
	v_cndmask_b32_e64 v88, v88, v89, s[40:41]
	v_sub_f32_e32 v89, v111, v86
	v_mul_f32_e32 v90, 0x3fb8aa3b, v89
	v_fma_f32 v91, v89, s1, -v90
	v_rndne_f32_e32 v92, v90
	v_fmac_f32_e32 v91, 0x32a5705f, v89
	v_sub_f32_e32 v90, v90, v92
	v_add_f32_e32 v90, v90, v91
	v_exp_f32_e32 v90, v90
	v_cvt_i32_f32_e32 v91, v92
	v_cmp_ngt_f32_e32 vcc, s6, v89
	v_ldexp_f32 v90, v90, v91
	s_nop 0
	v_cndmask_b32_e32 v90, 0, v90, vcc
	v_cmp_nlt_f32_e32 vcc, s7, v89
	s_nop 1
	v_cndmask_b32_e32 v89, v173, v90, vcc
	v_add_f32_e32 v87, v89, v87
	v_cndmask_b32_e64 v88, v88, v89, s[42:43]
	v_sub_f32_e32 v89, v112, v86
	v_mul_f32_e32 v90, 0x3fb8aa3b, v89
	v_fma_f32 v91, v89, s1, -v90
	v_rndne_f32_e32 v92, v90
	v_fmac_f32_e32 v91, 0x32a5705f, v89
	v_sub_f32_e32 v90, v90, v92
	v_add_f32_e32 v90, v90, v91
	v_exp_f32_e32 v90, v90
	v_cvt_i32_f32_e32 v91, v92
	v_cmp_ngt_f32_e32 vcc, s6, v89
	v_ldexp_f32 v90, v90, v91
	s_nop 0
	v_cndmask_b32_e32 v90, 0, v90, vcc
	v_cmp_nlt_f32_e32 vcc, s7, v89
	s_nop 1
	v_cndmask_b32_e32 v89, v173, v90, vcc
	v_add_f32_e32 v87, v89, v87
	v_cndmask_b32_e64 v88, v88, v89, s[44:45]
	v_sub_f32_e32 v89, v113, v86
	v_mul_f32_e32 v90, 0x3fb8aa3b, v89
	v_fma_f32 v91, v89, s1, -v90
	v_rndne_f32_e32 v92, v90
	v_fmac_f32_e32 v91, 0x32a5705f, v89
	v_sub_f32_e32 v90, v90, v92
	v_add_f32_e32 v90, v90, v91
	v_exp_f32_e32 v90, v90
	v_cvt_i32_f32_e32 v91, v92
	v_cmp_ngt_f32_e32 vcc, s6, v89
	v_ldexp_f32 v90, v90, v91
	s_nop 0
	v_cndmask_b32_e32 v90, 0, v90, vcc
	v_cmp_nlt_f32_e32 vcc, s7, v89
	s_nop 1
	v_cndmask_b32_e32 v89, v173, v90, vcc
	v_add_f32_e32 v87, v89, v87
	v_cndmask_b32_e64 v88, v88, v89, s[46:47]
	v_sub_f32_e32 v89, v94, v86
	v_mul_f32_e32 v90, 0x3fb8aa3b, v89
	v_fma_f32 v91, v89, s1, -v90
	v_rndne_f32_e32 v92, v90
	v_fmac_f32_e32 v91, 0x32a5705f, v89
	v_sub_f32_e32 v90, v90, v92
	v_add_f32_e32 v90, v90, v91
	v_exp_f32_e32 v90, v90
	v_cvt_i32_f32_e32 v91, v92
	v_cmp_ngt_f32_e32 vcc, s6, v89
	v_ldexp_f32 v90, v90, v91
	s_nop 0
	v_cndmask_b32_e32 v90, 0, v90, vcc
	v_cmp_nlt_f32_e32 vcc, s7, v89
	s_nop 1
	v_cndmask_b32_e32 v89, v173, v90, vcc
	v_add_f32_e32 v87, v89, v87
	v_cndmask_b32_e64 v88, v88, v89, s[48:49]
	v_sub_f32_e32 v89, v95, v86
	v_mul_f32_e32 v90, 0x3fb8aa3b, v89
	v_fma_f32 v91, v89, s1, -v90
	v_rndne_f32_e32 v92, v90
	v_fmac_f32_e32 v91, 0x32a5705f, v89
	v_sub_f32_e32 v90, v90, v92
	v_add_f32_e32 v90, v90, v91
	v_exp_f32_e32 v90, v90
	v_cvt_i32_f32_e32 v91, v92
	v_cmp_ngt_f32_e32 vcc, s6, v89
	v_ldexp_f32 v90, v90, v91
	s_nop 0
	v_cndmask_b32_e32 v90, 0, v90, vcc
	v_cmp_nlt_f32_e32 vcc, s7, v89
	s_nop 1
	v_cndmask_b32_e32 v89, v173, v90, vcc
	v_add_f32_e32 v87, v89, v87
	v_cndmask_b32_e64 v88, v88, v89, s[50:51]
	v_sub_f32_e32 v89, v96, v86
	v_mul_f32_e32 v90, 0x3fb8aa3b, v89
	v_fma_f32 v91, v89, s1, -v90
	v_rndne_f32_e32 v92, v90
	v_fmac_f32_e32 v91, 0x32a5705f, v89
	v_sub_f32_e32 v90, v90, v92
	v_add_f32_e32 v90, v90, v91
	v_exp_f32_e32 v90, v90
	v_cvt_i32_f32_e32 v91, v92
	v_cmp_ngt_f32_e32 vcc, s6, v89
	v_ldexp_f32 v90, v90, v91
	s_nop 0
	v_cndmask_b32_e32 v90, 0, v90, vcc
	v_cmp_nlt_f32_e32 vcc, s7, v89
	s_nop 1
	v_cndmask_b32_e32 v89, v173, v90, vcc
	v_add_f32_e32 v87, v89, v87
	v_cndmask_b32_e64 v88, v88, v89, s[52:53]
	v_sub_f32_e32 v89, v97, v86
	v_mul_f32_e32 v90, 0x3fb8aa3b, v89
	v_fma_f32 v91, v89, s1, -v90
	v_rndne_f32_e32 v92, v90
	v_fmac_f32_e32 v91, 0x32a5705f, v89
	v_sub_f32_e32 v90, v90, v92
	v_add_f32_e32 v90, v90, v91
	v_exp_f32_e32 v90, v90
	v_cvt_i32_f32_e32 v91, v92
	v_cmp_ngt_f32_e32 vcc, s6, v89
	v_ldexp_f32 v90, v90, v91
	s_nop 0
	v_cndmask_b32_e32 v90, 0, v90, vcc
	v_cmp_nlt_f32_e32 vcc, s7, v89
	s_nop 1
	v_cndmask_b32_e32 v89, v173, v90, vcc
	v_add_f32_e32 v87, v89, v87
	v_cndmask_b32_e64 v88, v88, v89, s[54:55]
	v_mul_f32_e32 v89, 0x3fb8aa3b, v82
	v_fma_f32 v90, v82, s1, -v89
	v_rndne_f32_e32 v91, v89
	v_fmac_f32_e32 v90, 0x32a5705f, v82
	v_sub_f32_e32 v89, v89, v91
	v_add_f32_e32 v89, v89, v90
	v_exp_f32_e32 v89, v89
	v_cvt_i32_f32_e32 v90, v91
	v_cmp_ngt_f32_e32 vcc, s6, v82
	v_ldexp_f32 v89, v89, v90
	s_nop 0
	v_cndmask_b32_e32 v89, 0, v89, vcc
	v_cmp_nlt_f32_e32 vcc, s7, v82
	s_nop 1
	v_cndmask_b32_e32 v82, v173, v89, vcc
	v_add_f32_e32 v87, v82, v87
	v_cndmask_b32_e64 v82, v88, v82, s[56:57]
	v_mul_f32_e32 v88, 0x3fb8aa3b, v83
	v_fma_f32 v89, v83, s1, -v88
	v_rndne_f32_e32 v90, v88
	v_fmac_f32_e32 v89, 0x32a5705f, v83
	v_sub_f32_e32 v88, v88, v90
	v_add_f32_e32 v88, v88, v89
	v_exp_f32_e32 v88, v88
	v_cvt_i32_f32_e32 v89, v90
	v_cmp_ngt_f32_e32 vcc, s6, v83
	v_ldexp_f32 v88, v88, v89
	s_nop 0
	v_cndmask_b32_e32 v88, 0, v88, vcc
	v_cmp_nlt_f32_e32 vcc, s7, v83
	s_nop 1
	v_cndmask_b32_e32 v83, v173, v88, vcc
	v_add_f32_e32 v87, v83, v87
	v_cndmask_b32_e64 v82, v82, v83, s[58:59]
	v_sub_f32_e32 v83, v84, v86
	v_mul_f32_e32 v84, 0x3fb8aa3b, v83
	v_fma_f32 v88, v83, s1, -v84
	v_rndne_f32_e32 v89, v84
	v_fmac_f32_e32 v88, 0x32a5705f, v83
	v_sub_f32_e32 v84, v84, v89
	v_add_f32_e32 v84, v84, v88
	v_exp_f32_e32 v84, v84
	v_cvt_i32_f32_e32 v88, v89
	v_cmp_ngt_f32_e32 vcc, s6, v83
	v_ldexp_f32 v84, v84, v88
	s_nop 0
	v_cndmask_b32_e32 v84, 0, v84, vcc
	v_cmp_nlt_f32_e32 vcc, s7, v83
	s_nop 1
	v_cndmask_b32_e32 v83, v173, v84, vcc
	v_add_f32_e32 v84, v83, v87
	v_cndmask_b32_e64 v82, v82, v83, s[60:61]
	v_sub_f32_e32 v83, v85, v86
	v_mul_f32_e32 v85, 0x3fb8aa3b, v83
	v_fma_f32 v86, v83, s1, -v85
	v_rndne_f32_e32 v87, v85
	v_fmac_f32_e32 v86, 0x32a5705f, v83
	v_sub_f32_e32 v85, v85, v87
	v_add_f32_e32 v85, v85, v86
	v_exp_f32_e32 v85, v85
	v_cvt_i32_f32_e32 v86, v87
	v_cmp_ngt_f32_e32 vcc, s6, v83
	v_ldexp_f32 v85, v85, v86
	s_nop 0
	v_cndmask_b32_e32 v85, 0, v85, vcc
	v_cmp_nlt_f32_e32 vcc, s7, v83
	s_nop 1
	v_cndmask_b32_e32 v83, v173, v85, vcc
	v_add_f32_e32 v84, v83, v84
	v_cndmask_b32_e64 v82, v82, v83, s[62:63]
	v_div_scale_f32 v83, s[64:65], v84, v84, v82
	v_rcp_f32_e32 v85, v83
	s_nop 0
	v_fma_f32 v86, -v83, v85, 1.0
	v_fmac_f32_e32 v85, v86, v85
	v_div_scale_f32 v86, vcc, v82, v84, v82
	v_mul_f32_e32 v87, v86, v85
	v_fma_f32 v88, -v83, v87, v86
	v_fmac_f32_e32 v87, v88, v85
	v_fma_f32 v83, -v83, v87, v86
	v_div_fmas_f32 v83, v83, v85, v87
	v_div_fixup_f32 v82, v83, v84, v82
	v_lshl_add_u64 v[84:85], v[154:155], 0, s[86:87]
	v_subrev_co_u32_e32 v84, vcc, 0, v84
	s_add_u32 s86, s86, 0x200
	s_nop 0
	v_subb_co_u32_e32 v85, vcc, v85, v82, vcc
	v_add_u32_e32 v82, s86, v0
	v_add_u32_e32 v82, 0xfffffe01, v82
	s_addc_u32 s87, s87, 0
	v_cmp_lt_u32_e32 vcc, s3, v82
	ds_write_b64 v177, v[84:85]
	ds_write2st64_b32 v134, v167, v179 offset1:32
	v_add_u32_e32 v134, 0x800, v134
	v_add_u32_e32 v177, 0x1000, v177
	v_lshl_add_u64 v[98:99], s[82:83], 0, v[158:159]
	v_add_co_u32_e32 v86, vcc, 0x7400000, v98
	v_lshl_add_u64 v[100:101], s[82:83], 0, v[156:157]
	s_nop 0
	v_addc_co_u32_e32 v87, vcc, 0, v99, vcc
	s_mov_b64 s[64:65], 0x7000000
	v_add_co_u32_e32 v90, vcc, 0x7000000, v100
	v_lshl_add_u64 v[88:89], v[100:101], 0, s[64:65]
	s_nop 0
	v_addc_co_u32_e32 v91, vcc, 0, v101, vcc
	s_mov_b32 s3, 0x7410000
	global_load_dwordx4 v[82:85], v[88:89], off offset:48
	global_load_dwordx4 v[94:97], v[88:89], off offset:32
	global_load_dword v179, v[86:87], off
	global_load_dwordx4 v[110:113], v[88:89], off offset:16
	v_add_co_u32_e32 v86, vcc, s3, v98
	s_mov_b32 s3, 0x7100000
	s_nop 0
	v_addc_co_u32_e32 v87, vcc, 0, v99, vcc
	global_load_dwordx4 v[126:129], v[90:91], off
	global_load_dword v196, v[86:87], off
	v_add_co_u32_e32 v86, vcc, s3, v100
	s_mov_b32 s3, 0x7420000
	s_nop 0
	v_addc_co_u32_e32 v87, vcc, 0, v101, vcc
	v_add_co_u32_e32 v114, vcc, s3, v98
	s_mov_b32 s3, 0x7200000
	s_nop 0
	v_addc_co_u32_e32 v115, vcc, 0, v99, vcc
	v_add_co_u32_e32 v184, vcc, s3, v100
	s_mov_b64 s[64:65], 0x7100000
	s_nop 0
	v_addc_co_u32_e32 v185, vcc, 0, v101, vcc
	s_mov_b32 s3, 0x7430000
	v_lshl_add_u64 v[90:91], v[100:101], 0, s[64:65]
	s_mov_b64 s[64:65], 0x7200000
	v_add_co_u32_e32 v98, vcc, s3, v98
	v_lshl_add_u64 v[116:117], v[100:101], 0, s[64:65]
	s_nop 0
	v_addc_co_u32_e32 v99, vcc, 0, v99, vcc
	s_mov_b32 s3, 0x7300000
	global_load_dwordx4 v[180:183], v[86:87], off
	s_nop 0
	global_load_dwordx4 v[86:89], v[90:91], off offset:48
	global_load_dwordx4 v[102:105], v[90:91], off offset:32
	global_load_dwordx4 v[118:121], v[90:91], off offset:16
	s_nop 0
	global_load_dwordx4 v[90:93], v[116:117], off offset:48
	global_load_dwordx4 v[106:109], v[116:117], off offset:32
	global_load_dword v197, v[114:115], off
	global_load_dwordx4 v[122:125], v[116:117], off offset:16
	s_nop 0
	global_load_dwordx4 v[184:187], v[184:185], off
	s_nop 0
	global_load_dword v198, v[98:99], off
	s_mov_b64 s[64:65], 0x7300000
	v_add_co_u32_e32 v98, vcc, s3, v100
	v_lshl_add_u64 v[192:193], v[100:101], 0, s[64:65]
	s_nop 0
	v_addc_co_u32_e32 v99, vcc, 0, v101, vcc
	global_load_dwordx4 v[188:191], v[98:99], off
	s_nop 0
	global_load_dwordx4 v[98:101], v[192:193], off offset:48
	global_load_dwordx4 v[114:117], v[192:193], off offset:32
	s_nop 0
	global_load_dwordx4 v[192:195], v[192:193], off offset:16
	v_lshl_add_u64 v[158:159], v[158:159], 0, s[96:97]
	v_lshl_add_u64 v[156:157], v[156:157], 0, s[14:15]
	s_waitcnt vmcnt(34)
	v_add_f32_e32 v201, v201, v218
	s_waitcnt vmcnt(24)
	v_add_f32_e32 v218, v219, v220
	v_add_f32_e32 v201, v201, v218
	v_fmamk_f32 v201, v201, 0x3a800000, v166
	s_mov_b32 s3, 0xf800000
	v_cmp_gt_f32_e32 vcc, s3, v201
	v_mul_f32_e32 v218, 0x4f800000, v201
	v_add_f32_e32 v46, v46, v202
	v_cndmask_b32_e32 v201, v201, v218, vcc
	v_sqrt_f32_e32 v218, v201
	s_waitcnt vmcnt(23)
	v_add_f32_e32 v202, v206, v210
	v_add_f32_e32 v46, v46, v202
	v_add_f32_e32 v47, v47, v203
	v_add_u32_e32 v219, -1, v218
	v_fma_f32 v220, -v219, v218, v201
	v_cmp_ge_f32_e64 s[64:65], 0, v220
	v_add_u32_e32 v220, 1, v218
	v_add_f32_e32 v202, v207, v211
	v_cndmask_b32_e64 v219, v218, v219, s[64:65]
	v_fma_f32 v218, -v220, v218, v201
	v_cmp_lt_f32_e64 s[64:65], 0, v218
	v_add_f32_e32 v2, v2, v6
	s_waitcnt vmcnt(22)
	v_add_f32_e32 v6, v10, v18
	v_cndmask_b32_e64 v218, v219, v220, s[64:65]
	v_mul_f32_e32 v219, 0x37800000, v218
	v_cndmask_b32_e32 v218, v218, v219, vcc
	v_cmp_class_f32_e32 vcc, v201, v168
	v_add_f32_e32 v47, v47, v202
	v_add_f32_e32 v48, v48, v204
	v_cndmask_b32_e32 v201, v218, v201, vcc
	v_div_scale_f32 v218, s[64:65], v201, v201, 1.0
	v_rcp_f32_e32 v219, v218
	v_add_f32_e32 v202, v208, v212
	v_add_f32_e32 v30, v30, v38
	s_waitcnt vmcnt(20)
	v_add_f32_e32 v38, v42, v214
	v_fma_f32 v220, -v218, v219, 1.0
	v_fmac_f32_e32 v219, v220, v219
	v_div_scale_f32 v220, vcc, 1.0, v201, 1.0
	v_mul_f32_e32 v221, v220, v219
	v_fma_f32 v222, -v218, v221, v220
	v_fmac_f32_e32 v221, v222, v219
	v_fma_f32 v218, -v218, v221, v220
	v_div_fmas_f32 v218, v218, v219, v221
	v_add_f32_e32 v2, v2, v6
	v_add_f32_e32 v3, v3, v7
	v_add_f32_e32 v6, v11, v19
	v_div_fixup_f32 v201, v218, v201, 1.0
	v_add_f32_e32 v48, v48, v202
	v_add_f32_e32 v49, v49, v205
	v_add_f32_e32 v202, v209, v213
	v_add_f32_e32 v30, v30, v38
	v_add_f32_e32 v31, v31, v39
	v_add_f32_e32 v38, v43, v215
	v_add_f32_e32 v3, v3, v6
	v_add_f32_e32 v4, v4, v8
	v_add_f32_e32 v6, v12, v20
	v_fma_f32 v46, v46, v201, v66
	v_fma_f32 v47, v47, v201, v67
	v_add_f32_e32 v49, v49, v202
	v_add_f32_e32 v31, v31, v38
	v_add_f32_e32 v32, v32, v40
	v_add_f32_e32 v38, v44, v216
	v_add_f32_e32 v14, v14, v22
	v_add_f32_e32 v22, v26, v34
	v_add_f32_e32 v4, v4, v6
	v_add_f32_e32 v5, v5, v9
	v_add_f32_e32 v6, v13, v21
	v_fma_f32 v48, v48, v201, v68
	v_fma_f32 v49, v49, v201, v69
	v_add_f32_e32 v32, v32, v38
	v_add_f32_e32 v33, v33, v41
	v_add_f32_e32 v38, v45, v217
	v_add_f32_e32 v14, v14, v22
	v_add_f32_e32 v15, v15, v23
	v_add_f32_e32 v22, v27, v35
	v_add_f32_e32 v5, v5, v6
	v_max_f32_e32 v6, v46, v47
	v_fma_f32 v30, v30, v201, v70
	v_fma_f32 v31, v31, v201, v71
	v_add_f32_e32 v33, v33, v38
	v_add_f32_e32 v15, v15, v22
	v_add_f32_e32 v16, v16, v24
	v_add_f32_e32 v22, v28, v36
	v_max3_f32 v6, v6, v48, v49
	v_fma_f32 v32, v32, v201, v72
	v_fma_f32 v33, v33, v201, v73
	v_add_f32_e32 v16, v16, v22
	v_add_f32_e32 v17, v17, v25
	v_add_f32_e32 v22, v29, v37
	v_max3_f32 v6, v6, v30, v31
	v_fma_f32 v14, v201, v14, v74
	v_fma_f32 v15, v201, v15, v75
	v_add_f32_e32 v17, v17, v22
	v_max3_f32 v6, v6, v32, v33
	v_fma_f32 v16, v201, v16, v76
	v_fma_f32 v17, v201, v17, v77
	v_max3_f32 v6, v6, v14, v15
	v_fma_f32 v2, v201, v2, v78
	v_fma_f32 v3, v201, v3, v79
	v_max3_f32 v6, v6, v16, v17
	v_fma_f32 v4, v201, v4, v80
	v_fma_f32 v5, v201, v5, v81
	v_max3_f32 v6, v6, v2, v3
	v_max3_f32 v6, v6, v4, v5
	v_sub_f32_e32 v7, v46, v6
	v_mul_f32_e32 v8, 0x3fb8aa3b, v7
	v_fma_f32 v9, v7, s1, -v8
	v_rndne_f32_e32 v10, v8
	v_fmac_f32_e32 v9, 0x32a5705f, v7
	v_sub_f32_e32 v8, v8, v10
	v_add_f32_e32 v8, v8, v9
	v_exp_f32_e32 v8, v8
	v_cvt_i32_f32_e32 v9, v10
	v_cmp_ngt_f32_e32 vcc, s6, v7
	v_sub_f32_e32 v2, v2, v6
	v_sub_f32_e32 v3, v3, v6
	v_ldexp_f32 v8, v8, v9
	v_sub_f32_e32 v9, v47, v6
	v_mul_f32_e32 v10, 0x3fb8aa3b, v9
	v_fma_f32 v11, v9, s1, -v10
	v_rndne_f32_e32 v12, v10
	v_fmac_f32_e32 v11, 0x32a5705f, v9
	v_sub_f32_e32 v10, v10, v12
	v_add_f32_e32 v10, v10, v11
	v_exp_f32_e32 v10, v10
	v_cvt_i32_f32_e32 v11, v12
	v_cndmask_b32_e32 v8, 0, v8, vcc
	v_cmp_nlt_f32_e32 vcc, s7, v7
	s_movk_i32 s3, 0x5ff
	v_ldexp_f32 v10, v10, v11
	v_cndmask_b32_e32 v7, v173, v8, vcc
	v_cmp_ngt_f32_e32 vcc, s6, v9
	v_cndmask_b32_e64 v8, 0, v7, s[30:31]
	v_cndmask_b32_e32 v10, 0, v10, vcc
	v_cmp_nlt_f32_e32 vcc, s7, v9
	s_nop 0
	v_cndmask_b32_e32 v9, v173, v10, vcc
	v_add_f32_e32 v7, v7, v9
	v_cndmask_b32_e64 v8, v8, v9, s[34:35]
	v_sub_f32_e32 v9, v48, v6
	v_mul_f32_e32 v10, 0x3fb8aa3b, v9
	v_fma_f32 v11, v9, s1, -v10
	v_rndne_f32_e32 v12, v10
	v_fmac_f32_e32 v11, 0x32a5705f, v9
	v_sub_f32_e32 v10, v10, v12
	v_add_f32_e32 v10, v10, v11
	v_exp_f32_e32 v10, v10
	v_cvt_i32_f32_e32 v11, v12
	v_cmp_ngt_f32_e32 vcc, s6, v9
	v_ldexp_f32 v10, v10, v11
	s_nop 0
	v_cndmask_b32_e32 v10, 0, v10, vcc
	v_cmp_nlt_f32_e32 vcc, s7, v9
	s_nop 1
	v_cndmask_b32_e32 v9, v173, v10, vcc
	v_add_f32_e32 v7, v9, v7
	v_cndmask_b32_e64 v8, v8, v9, s[36:37]
	v_sub_f32_e32 v9, v49, v6
	v_mul_f32_e32 v10, 0x3fb8aa3b, v9
	v_fma_f32 v11, v9, s1, -v10
	v_rndne_f32_e32 v12, v10
	v_fmac_f32_e32 v11, 0x32a5705f, v9
	v_sub_f32_e32 v10, v10, v12
	v_add_f32_e32 v10, v10, v11
	v_exp_f32_e32 v10, v10
	v_cvt_i32_f32_e32 v11, v12
	v_cmp_ngt_f32_e32 vcc, s6, v9
	v_ldexp_f32 v10, v10, v11
	s_nop 0
	v_cndmask_b32_e32 v10, 0, v10, vcc
	v_cmp_nlt_f32_e32 vcc, s7, v9
	s_nop 1
	v_cndmask_b32_e32 v9, v173, v10, vcc
	v_add_f32_e32 v7, v9, v7
	v_cndmask_b32_e64 v8, v8, v9, s[38:39]
	v_sub_f32_e32 v9, v30, v6
	v_mul_f32_e32 v10, 0x3fb8aa3b, v9
	v_fma_f32 v11, v9, s1, -v10
	v_rndne_f32_e32 v12, v10
	v_fmac_f32_e32 v11, 0x32a5705f, v9
	v_sub_f32_e32 v10, v10, v12
	v_add_f32_e32 v10, v10, v11
	v_exp_f32_e32 v10, v10
	v_cvt_i32_f32_e32 v11, v12
	v_cmp_ngt_f32_e32 vcc, s6, v9
	v_ldexp_f32 v10, v10, v11
	s_nop 0
	v_cndmask_b32_e32 v10, 0, v10, vcc
	v_cmp_nlt_f32_e32 vcc, s7, v9
	s_nop 1
	v_cndmask_b32_e32 v9, v173, v10, vcc
	v_add_f32_e32 v7, v9, v7
	v_cndmask_b32_e64 v8, v8, v9, s[40:41]
	v_sub_f32_e32 v9, v31, v6
	v_mul_f32_e32 v10, 0x3fb8aa3b, v9
	v_fma_f32 v11, v9, s1, -v10
	v_rndne_f32_e32 v12, v10
	v_fmac_f32_e32 v11, 0x32a5705f, v9
	v_sub_f32_e32 v10, v10, v12
	v_add_f32_e32 v10, v10, v11
	v_exp_f32_e32 v10, v10
	v_cvt_i32_f32_e32 v11, v12
	v_cmp_ngt_f32_e32 vcc, s6, v9
	v_ldexp_f32 v10, v10, v11
	s_nop 0
	v_cndmask_b32_e32 v10, 0, v10, vcc
	v_cmp_nlt_f32_e32 vcc, s7, v9
	s_nop 1
	v_cndmask_b32_e32 v9, v173, v10, vcc
	v_add_f32_e32 v7, v9, v7
	v_cndmask_b32_e64 v8, v8, v9, s[42:43]
	v_sub_f32_e32 v9, v32, v6
	v_mul_f32_e32 v10, 0x3fb8aa3b, v9
	v_fma_f32 v11, v9, s1, -v10
	v_rndne_f32_e32 v12, v10
	v_fmac_f32_e32 v11, 0x32a5705f, v9
	v_sub_f32_e32 v10, v10, v12
	v_add_f32_e32 v10, v10, v11
	v_exp_f32_e32 v10, v10
	v_cvt_i32_f32_e32 v11, v12
	v_cmp_ngt_f32_e32 vcc, s6, v9
	v_ldexp_f32 v10, v10, v11
	s_nop 0
	v_cndmask_b32_e32 v10, 0, v10, vcc
	v_cmp_nlt_f32_e32 vcc, s7, v9
	s_nop 1
	v_cndmask_b32_e32 v9, v173, v10, vcc
	v_add_f32_e32 v7, v9, v7
	v_cndmask_b32_e64 v8, v8, v9, s[44:45]
	v_sub_f32_e32 v9, v33, v6
	v_mul_f32_e32 v10, 0x3fb8aa3b, v9
	v_fma_f32 v11, v9, s1, -v10
	v_rndne_f32_e32 v12, v10
	v_fmac_f32_e32 v11, 0x32a5705f, v9
	v_sub_f32_e32 v10, v10, v12
	v_add_f32_e32 v10, v10, v11
	v_exp_f32_e32 v10, v10
	v_cvt_i32_f32_e32 v11, v12
	v_cmp_ngt_f32_e32 vcc, s6, v9
	v_ldexp_f32 v10, v10, v11
	s_nop 0
	v_cndmask_b32_e32 v10, 0, v10, vcc
	v_cmp_nlt_f32_e32 vcc, s7, v9
	s_nop 1
	v_cndmask_b32_e32 v9, v173, v10, vcc
	v_add_f32_e32 v7, v9, v7
	v_cndmask_b32_e64 v8, v8, v9, s[46:47]
	v_sub_f32_e32 v9, v14, v6
	v_mul_f32_e32 v10, 0x3fb8aa3b, v9
	v_fma_f32 v11, v9, s1, -v10
	v_rndne_f32_e32 v12, v10
	v_fmac_f32_e32 v11, 0x32a5705f, v9
	v_sub_f32_e32 v10, v10, v12
	v_add_f32_e32 v10, v10, v11
	v_exp_f32_e32 v10, v10
	v_cvt_i32_f32_e32 v11, v12
	v_cmp_ngt_f32_e32 vcc, s6, v9
	v_ldexp_f32 v10, v10, v11
	s_nop 0
	v_cndmask_b32_e32 v10, 0, v10, vcc
	v_cmp_nlt_f32_e32 vcc, s7, v9
	s_nop 1
	v_cndmask_b32_e32 v9, v173, v10, vcc
	v_add_f32_e32 v7, v9, v7
	v_cndmask_b32_e64 v8, v8, v9, s[48:49]
	v_sub_f32_e32 v9, v15, v6
	v_mul_f32_e32 v10, 0x3fb8aa3b, v9
	v_fma_f32 v11, v9, s1, -v10
	v_rndne_f32_e32 v12, v10
	v_fmac_f32_e32 v11, 0x32a5705f, v9
	v_sub_f32_e32 v10, v10, v12
	v_add_f32_e32 v10, v10, v11
	v_exp_f32_e32 v10, v10
	v_cvt_i32_f32_e32 v11, v12
	v_cmp_ngt_f32_e32 vcc, s6, v9
	v_ldexp_f32 v10, v10, v11
	s_nop 0
	v_cndmask_b32_e32 v10, 0, v10, vcc
	v_cmp_nlt_f32_e32 vcc, s7, v9
	s_nop 1
	v_cndmask_b32_e32 v9, v173, v10, vcc
	v_add_f32_e32 v7, v9, v7
	v_cndmask_b32_e64 v8, v8, v9, s[50:51]
	v_sub_f32_e32 v9, v16, v6
	v_mul_f32_e32 v10, 0x3fb8aa3b, v9
	v_fma_f32 v11, v9, s1, -v10
	v_rndne_f32_e32 v12, v10
	v_fmac_f32_e32 v11, 0x32a5705f, v9
	v_sub_f32_e32 v10, v10, v12
	v_add_f32_e32 v10, v10, v11
	v_exp_f32_e32 v10, v10
	v_cvt_i32_f32_e32 v11, v12
	v_cmp_ngt_f32_e32 vcc, s6, v9
	v_ldexp_f32 v10, v10, v11
	s_nop 0
	v_cndmask_b32_e32 v10, 0, v10, vcc
	v_cmp_nlt_f32_e32 vcc, s7, v9
	s_nop 1
	v_cndmask_b32_e32 v9, v173, v10, vcc
	v_add_f32_e32 v7, v9, v7
	v_cndmask_b32_e64 v8, v8, v9, s[52:53]
	v_sub_f32_e32 v9, v17, v6
	v_mul_f32_e32 v10, 0x3fb8aa3b, v9
	v_fma_f32 v11, v9, s1, -v10
	v_rndne_f32_e32 v12, v10
	v_fmac_f32_e32 v11, 0x32a5705f, v9
	v_sub_f32_e32 v10, v10, v12
	v_add_f32_e32 v10, v10, v11
	v_exp_f32_e32 v10, v10
	v_cvt_i32_f32_e32 v11, v12
	v_cmp_ngt_f32_e32 vcc, s6, v9
	v_ldexp_f32 v10, v10, v11
	s_nop 0
	v_cndmask_b32_e32 v10, 0, v10, vcc
	v_cmp_nlt_f32_e32 vcc, s7, v9
	s_nop 1
	v_cndmask_b32_e32 v9, v173, v10, vcc
	v_add_f32_e32 v7, v9, v7
	v_cndmask_b32_e64 v8, v8, v9, s[54:55]
	v_mul_f32_e32 v9, 0x3fb8aa3b, v2
	v_fma_f32 v10, v2, s1, -v9
	v_rndne_f32_e32 v11, v9
	v_fmac_f32_e32 v10, 0x32a5705f, v2
	v_sub_f32_e32 v9, v9, v11
	v_add_f32_e32 v9, v9, v10
	v_exp_f32_e32 v9, v9
	v_cvt_i32_f32_e32 v10, v11
	v_cmp_ngt_f32_e32 vcc, s6, v2
	v_ldexp_f32 v9, v9, v10
	s_nop 0
	v_cndmask_b32_e32 v9, 0, v9, vcc
	v_cmp_nlt_f32_e32 vcc, s7, v2
	s_nop 1
	v_cndmask_b32_e32 v2, v173, v9, vcc
	v_add_f32_e32 v7, v2, v7
	v_cndmask_b32_e64 v2, v8, v2, s[56:57]
	v_mul_f32_e32 v8, 0x3fb8aa3b, v3
	v_fma_f32 v9, v3, s1, -v8
	v_rndne_f32_e32 v10, v8
	v_fmac_f32_e32 v9, 0x32a5705f, v3
	v_sub_f32_e32 v8, v8, v10
	v_add_f32_e32 v8, v8, v9
	v_exp_f32_e32 v8, v8
	v_cvt_i32_f32_e32 v9, v10
	v_cmp_ngt_f32_e32 vcc, s6, v3
	v_ldexp_f32 v8, v8, v9
	s_nop 0
	v_cndmask_b32_e32 v8, 0, v8, vcc
	v_cmp_nlt_f32_e32 vcc, s7, v3
	s_nop 1
	v_cndmask_b32_e32 v3, v173, v8, vcc
	v_add_f32_e32 v7, v3, v7
	v_cndmask_b32_e64 v2, v2, v3, s[58:59]
	v_sub_f32_e32 v3, v4, v6
	v_mul_f32_e32 v4, 0x3fb8aa3b, v3
	v_fma_f32 v8, v3, s1, -v4
	v_rndne_f32_e32 v9, v4
	v_fmac_f32_e32 v8, 0x32a5705f, v3
	v_sub_f32_e32 v4, v4, v9
	v_add_f32_e32 v4, v4, v8
	v_exp_f32_e32 v4, v4
	v_cvt_i32_f32_e32 v8, v9
	v_cmp_ngt_f32_e32 vcc, s6, v3
	v_ldexp_f32 v4, v4, v8
	s_nop 0
	v_cndmask_b32_e32 v4, 0, v4, vcc
	v_cmp_nlt_f32_e32 vcc, s7, v3
	s_nop 1
	v_cndmask_b32_e32 v3, v173, v4, vcc
	v_add_f32_e32 v4, v3, v7
	v_cndmask_b32_e64 v2, v2, v3, s[60:61]
	v_sub_f32_e32 v3, v5, v6
	v_mul_f32_e32 v5, 0x3fb8aa3b, v3
	v_fma_f32 v6, v3, s1, -v5
	v_rndne_f32_e32 v7, v5
	v_fmac_f32_e32 v6, 0x32a5705f, v3
	v_sub_f32_e32 v5, v5, v7
	v_add_f32_e32 v5, v5, v6
	v_exp_f32_e32 v5, v5
	v_cvt_i32_f32_e32 v6, v7
	v_cmp_ngt_f32_e32 vcc, s6, v3
	v_ldexp_f32 v5, v5, v6
	s_nop 0
	v_cndmask_b32_e32 v5, 0, v5, vcc
	v_cmp_nlt_f32_e32 vcc, s7, v3
	s_nop 1
	v_cndmask_b32_e32 v3, v173, v5, vcc
	v_add_f32_e32 v4, v3, v4
	v_cndmask_b32_e64 v2, v2, v3, s[62:63]
	v_div_scale_f32 v3, s[64:65], v4, v4, v2
	v_rcp_f32_e32 v5, v3
	s_nop 0
	v_fma_f32 v6, -v3, v5, 1.0
	v_fmac_f32_e32 v5, v6, v5
	v_div_scale_f32 v6, vcc, v2, v4, v2
	v_mul_f32_e32 v7, v6, v5
	v_fma_f32 v8, -v3, v7, v6
	v_fmac_f32_e32 v7, v8, v5
	v_fma_f32 v3, -v3, v7, v6
	v_div_fmas_f32 v3, v3, v5, v7
	v_div_fixup_f32 v2, v3, v4, v2
	v_lshl_add_u64 v[4:5], v[154:155], 0, s[86:87]
	v_subrev_co_u32_e32 v4, vcc, 0, v4
	s_add_u32 s86, s86, 0x200
	s_nop 0
	v_subb_co_u32_e32 v5, vcc, v5, v2, vcc
	v_add_u32_e32 v2, s86, v0
	v_add_u32_e32 v2, 0xfffffe01, v2
	s_addc_u32 s87, s87, 0
	v_cmp_lt_u32_e32 vcc, s3, v2
	ds_write_b64 v177, v[4:5]
	ds_write2st64_b32 v134, v167, v201 offset1:32
	v_add_u32_e32 v134, 0x800, v134
	v_add_u32_e32 v177, 0x1000, v177
	v_lshl_add_u64 v[18:19], s[82:83], 0, v[158:159]
	v_add_co_u32_e32 v6, vcc, 0x7400000, v18
	v_lshl_add_u64 v[20:21], s[82:83], 0, v[156:157]
	s_nop 0
	v_addc_co_u32_e32 v7, vcc, 0, v19, vcc
	s_mov_b64 s[64:65], 0x7000000
	v_add_co_u32_e32 v10, vcc, 0x7000000, v20
	v_lshl_add_u64 v[8:9], v[20:21], 0, s[64:65]
	s_nop 0
	v_addc_co_u32_e32 v11, vcc, 0, v21, vcc
	s_mov_b32 s3, 0x7410000
	global_load_dwordx4 v[2:5], v[8:9], off offset:48
	global_load_dwordx4 v[14:17], v[8:9], off offset:32
	global_load_dword v201, v[6:7], off
	global_load_dwordx4 v[30:33], v[8:9], off offset:16
	v_add_co_u32_e32 v6, vcc, s3, v18
	s_mov_b32 s3, 0x7100000
	s_nop 0
	v_addc_co_u32_e32 v7, vcc, 0, v19, vcc
	global_load_dwordx4 v[46:49], v[10:11], off
	global_load_dword v218, v[6:7], off
	v_add_co_u32_e32 v6, vcc, s3, v20
	s_mov_b32 s3, 0x7420000
	s_nop 0
	v_addc_co_u32_e32 v7, vcc, 0, v21, vcc
	v_add_co_u32_e32 v34, vcc, s3, v18
	s_mov_b32 s3, 0x7200000
	s_nop 0
	v_addc_co_u32_e32 v35, vcc, 0, v19, vcc
	v_add_co_u32_e32 v206, vcc, s3, v20
	s_mov_b64 s[64:65], 0x7100000
	s_nop 0
	v_addc_co_u32_e32 v207, vcc, 0, v21, vcc
	s_mov_b32 s3, 0x7430000
	v_lshl_add_u64 v[10:11], v[20:21], 0, s[64:65]
	s_mov_b64 s[64:65], 0x7200000
	v_add_co_u32_e32 v18, vcc, s3, v18
	v_lshl_add_u64 v[36:37], v[20:21], 0, s[64:65]
	s_nop 0
	v_addc_co_u32_e32 v19, vcc, 0, v19, vcc
	s_mov_b32 s3, 0x7300000
	global_load_dwordx4 v[202:205], v[6:7], off
	s_nop 0
	global_load_dwordx4 v[6:9], v[10:11], off offset:48
	global_load_dwordx4 v[22:25], v[10:11], off offset:32
	global_load_dwordx4 v[38:41], v[10:11], off offset:16
	s_nop 0
	global_load_dwordx4 v[10:13], v[36:37], off offset:48
	global_load_dwordx4 v[26:29], v[36:37], off offset:32
	global_load_dword v219, v[34:35], off
	global_load_dwordx4 v[42:45], v[36:37], off offset:16
	s_nop 0
	global_load_dwordx4 v[206:209], v[206:207], off
	s_nop 0
	global_load_dword v220, v[18:19], off
	s_mov_b64 s[64:65], 0x7300000
	v_add_co_u32_e32 v18, vcc, s3, v20
	v_lshl_add_u64 v[214:215], v[20:21], 0, s[64:65]
	s_nop 0
	v_addc_co_u32_e32 v19, vcc, 0, v21, vcc
	global_load_dwordx4 v[210:213], v[18:19], off
	s_nop 0
	global_load_dwordx4 v[18:21], v[214:215], off offset:48
	global_load_dwordx4 v[34:37], v[214:215], off offset:32
	s_nop 0
	global_load_dwordx4 v[214:217], v[214:215], off offset:16
	v_lshl_add_u64 v[158:159], v[158:159], 0, s[96:97]
	v_lshl_add_u64 v[156:157], v[156:157], 0, s[14:15]
	s_waitcnt vmcnt(34)
	v_add_f32_e32 v179, v179, v196
	s_waitcnt vmcnt(24)
	v_add_f32_e32 v196, v197, v198
	v_add_f32_e32 v179, v179, v196
	v_fmamk_f32 v179, v179, 0x3a800000, v166
	s_mov_b32 s3, 0xf800000
	v_cmp_gt_f32_e32 vcc, s3, v179
	v_mul_f32_e32 v196, 0x4f800000, v179
	v_add_f32_e32 v126, v126, v180
	v_cndmask_b32_e32 v179, v179, v196, vcc
	v_sqrt_f32_e32 v196, v179
	s_waitcnt vmcnt(23)
	v_add_f32_e32 v180, v184, v188
	v_add_f32_e32 v126, v126, v180
	v_add_f32_e32 v127, v127, v181
	v_add_u32_e32 v197, -1, v196
	v_fma_f32 v198, -v197, v196, v179
	v_cmp_ge_f32_e64 s[64:65], 0, v198
	v_add_u32_e32 v198, 1, v196
	v_add_f32_e32 v180, v185, v189
	v_cndmask_b32_e64 v197, v196, v197, s[64:65]
	v_fma_f32 v196, -v198, v196, v179
	v_cmp_lt_f32_e64 s[64:65], 0, v196
	v_add_f32_e32 v82, v82, v86
	s_waitcnt vmcnt(22)
	v_add_f32_e32 v86, v90, v98
	v_cndmask_b32_e64 v196, v197, v198, s[64:65]
	v_mul_f32_e32 v197, 0x37800000, v196
	v_cndmask_b32_e32 v196, v196, v197, vcc
	v_cmp_class_f32_e32 vcc, v179, v168
	v_add_f32_e32 v127, v127, v180
	v_add_f32_e32 v128, v128, v182
	v_cndmask_b32_e32 v179, v196, v179, vcc
	v_div_scale_f32 v196, s[64:65], v179, v179, 1.0
	v_rcp_f32_e32 v197, v196
	v_add_f32_e32 v180, v186, v190
	v_add_f32_e32 v110, v110, v118
	s_waitcnt vmcnt(20)
	v_add_f32_e32 v118, v122, v192
	v_fma_f32 v198, -v196, v197, 1.0
	v_fmac_f32_e32 v197, v198, v197
	v_div_scale_f32 v198, vcc, 1.0, v179, 1.0
	v_mul_f32_e32 v199, v198, v197
	v_fma_f32 v200, -v196, v199, v198
	v_fmac_f32_e32 v199, v200, v197
	v_fma_f32 v196, -v196, v199, v198
	v_div_fmas_f32 v196, v196, v197, v199
	v_add_f32_e32 v82, v82, v86
	v_add_f32_e32 v83, v83, v87
	v_add_f32_e32 v86, v91, v99
	v_div_fixup_f32 v179, v196, v179, 1.0
	v_add_f32_e32 v128, v128, v180
	v_add_f32_e32 v129, v129, v183
	v_add_f32_e32 v180, v187, v191
	v_add_f32_e32 v110, v110, v118
	v_add_f32_e32 v111, v111, v119
	v_add_f32_e32 v118, v123, v193
	v_add_f32_e32 v83, v83, v86
	v_add_f32_e32 v84, v84, v88
	v_add_f32_e32 v86, v92, v100
	v_fma_f32 v126, v126, v179, v66
	v_fma_f32 v127, v127, v179, v67
	v_add_f32_e32 v129, v129, v180
	v_add_f32_e32 v111, v111, v118
	v_add_f32_e32 v112, v112, v120
	v_add_f32_e32 v118, v124, v194
	v_add_f32_e32 v94, v94, v102
	v_add_f32_e32 v102, v106, v114
	v_add_f32_e32 v84, v84, v86
	v_add_f32_e32 v85, v85, v89
	v_add_f32_e32 v86, v93, v101
	v_fma_f32 v128, v128, v179, v68
	v_fma_f32 v129, v129, v179, v69
	v_add_f32_e32 v112, v112, v118
	v_add_f32_e32 v113, v113, v121
	v_add_f32_e32 v118, v125, v195
	v_add_f32_e32 v94, v94, v102
	v_add_f32_e32 v95, v95, v103
	v_add_f32_e32 v102, v107, v115
	v_add_f32_e32 v85, v85, v86
	v_max_f32_e32 v86, v126, v127
	v_fma_f32 v110, v110, v179, v70
	v_fma_f32 v111, v111, v179, v71
	v_add_f32_e32 v113, v113, v118
	v_add_f32_e32 v95, v95, v102
	v_add_f32_e32 v96, v96, v104
	v_add_f32_e32 v102, v108, v116
	v_max3_f32 v86, v86, v128, v129
	v_fma_f32 v112, v112, v179, v72
	v_fma_f32 v113, v113, v179, v73
	v_add_f32_e32 v96, v96, v102
	v_add_f32_e32 v97, v97, v105
	v_add_f32_e32 v102, v109, v117
	v_max3_f32 v86, v86, v110, v111
	v_fma_f32 v94, v179, v94, v74
	v_fma_f32 v95, v179, v95, v75
	v_add_f32_e32 v97, v97, v102
	v_max3_f32 v86, v86, v112, v113
	v_fma_f32 v96, v179, v96, v76
	v_fma_f32 v97, v179, v97, v77
	v_max3_f32 v86, v86, v94, v95
	v_fma_f32 v82, v179, v82, v78
	v_fma_f32 v83, v179, v83, v79
	v_max3_f32 v86, v86, v96, v97
	v_fma_f32 v84, v179, v84, v80
	v_fma_f32 v85, v179, v85, v81
	v_max3_f32 v86, v86, v82, v83
	v_max3_f32 v86, v86, v84, v85
	v_sub_f32_e32 v87, v126, v86
	v_mul_f32_e32 v88, 0x3fb8aa3b, v87
	v_fma_f32 v89, v87, s1, -v88
	v_rndne_f32_e32 v90, v88
	v_fmac_f32_e32 v89, 0x32a5705f, v87
	v_sub_f32_e32 v88, v88, v90
	v_add_f32_e32 v88, v88, v89
	v_exp_f32_e32 v88, v88
	v_cvt_i32_f32_e32 v89, v90
	v_cmp_ngt_f32_e32 vcc, s6, v87
	v_sub_f32_e32 v82, v82, v86
	v_sub_f32_e32 v83, v83, v86
	v_ldexp_f32 v88, v88, v89
	v_sub_f32_e32 v89, v127, v86
	v_mul_f32_e32 v90, 0x3fb8aa3b, v89
	v_fma_f32 v91, v89, s1, -v90
	v_rndne_f32_e32 v92, v90
	v_fmac_f32_e32 v91, 0x32a5705f, v89
	v_sub_f32_e32 v90, v90, v92
	v_add_f32_e32 v90, v90, v91
	v_exp_f32_e32 v90, v90
	v_cvt_i32_f32_e32 v91, v92
	v_cndmask_b32_e32 v88, 0, v88, vcc
	v_cmp_nlt_f32_e32 vcc, s7, v87
	s_movk_i32 s3, 0x5ff
	v_ldexp_f32 v90, v90, v91
	v_cndmask_b32_e32 v87, v173, v88, vcc
	v_cmp_ngt_f32_e32 vcc, s6, v89
	v_cndmask_b32_e64 v88, 0, v87, s[30:31]
	v_cndmask_b32_e32 v90, 0, v90, vcc
	v_cmp_nlt_f32_e32 vcc, s7, v89
	s_nop 0
	v_cndmask_b32_e32 v89, v173, v90, vcc
	v_add_f32_e32 v87, v87, v89
	v_cndmask_b32_e64 v88, v88, v89, s[34:35]
	v_sub_f32_e32 v89, v128, v86
	v_mul_f32_e32 v90, 0x3fb8aa3b, v89
	v_fma_f32 v91, v89, s1, -v90
	v_rndne_f32_e32 v92, v90
	v_fmac_f32_e32 v91, 0x32a5705f, v89
	v_sub_f32_e32 v90, v90, v92
	v_add_f32_e32 v90, v90, v91
	v_exp_f32_e32 v90, v90
	v_cvt_i32_f32_e32 v91, v92
	v_cmp_ngt_f32_e32 vcc, s6, v89
	v_ldexp_f32 v90, v90, v91
	s_nop 0
	v_cndmask_b32_e32 v90, 0, v90, vcc
	v_cmp_nlt_f32_e32 vcc, s7, v89
	s_nop 1
	v_cndmask_b32_e32 v89, v173, v90, vcc
	v_add_f32_e32 v87, v89, v87
	v_cndmask_b32_e64 v88, v88, v89, s[36:37]
	v_sub_f32_e32 v89, v129, v86
	v_mul_f32_e32 v90, 0x3fb8aa3b, v89
	v_fma_f32 v91, v89, s1, -v90
	v_rndne_f32_e32 v92, v90
	v_fmac_f32_e32 v91, 0x32a5705f, v89
	v_sub_f32_e32 v90, v90, v92
	v_add_f32_e32 v90, v90, v91
	v_exp_f32_e32 v90, v90
	v_cvt_i32_f32_e32 v91, v92
	v_cmp_ngt_f32_e32 vcc, s6, v89
	v_ldexp_f32 v90, v90, v91
	s_nop 0
	v_cndmask_b32_e32 v90, 0, v90, vcc
	v_cmp_nlt_f32_e32 vcc, s7, v89
	s_nop 1
	v_cndmask_b32_e32 v89, v173, v90, vcc
	v_add_f32_e32 v87, v89, v87
	v_cndmask_b32_e64 v88, v88, v89, s[38:39]
	v_sub_f32_e32 v89, v110, v86
	v_mul_f32_e32 v90, 0x3fb8aa3b, v89
	v_fma_f32 v91, v89, s1, -v90
	v_rndne_f32_e32 v92, v90
	v_fmac_f32_e32 v91, 0x32a5705f, v89
	v_sub_f32_e32 v90, v90, v92
	v_add_f32_e32 v90, v90, v91
	v_exp_f32_e32 v90, v90
	v_cvt_i32_f32_e32 v91, v92
	v_cmp_ngt_f32_e32 vcc, s6, v89
	v_ldexp_f32 v90, v90, v91
	s_nop 0
	v_cndmask_b32_e32 v90, 0, v90, vcc
	v_cmp_nlt_f32_e32 vcc, s7, v89
	s_nop 1
	v_cndmask_b32_e32 v89, v173, v90, vcc
	v_add_f32_e32 v87, v89, v87
	v_cndmask_b32_e64 v88, v88, v89, s[40:41]
	v_sub_f32_e32 v89, v111, v86
	v_mul_f32_e32 v90, 0x3fb8aa3b, v89
	v_fma_f32 v91, v89, s1, -v90
	v_rndne_f32_e32 v92, v90
	v_fmac_f32_e32 v91, 0x32a5705f, v89
	v_sub_f32_e32 v90, v90, v92
	v_add_f32_e32 v90, v90, v91
	v_exp_f32_e32 v90, v90
	v_cvt_i32_f32_e32 v91, v92
	v_cmp_ngt_f32_e32 vcc, s6, v89
	v_ldexp_f32 v90, v90, v91
	s_nop 0
	v_cndmask_b32_e32 v90, 0, v90, vcc
	v_cmp_nlt_f32_e32 vcc, s7, v89
	s_nop 1
	v_cndmask_b32_e32 v89, v173, v90, vcc
	v_add_f32_e32 v87, v89, v87
	v_cndmask_b32_e64 v88, v88, v89, s[42:43]
	v_sub_f32_e32 v89, v112, v86
	v_mul_f32_e32 v90, 0x3fb8aa3b, v89
	v_fma_f32 v91, v89, s1, -v90
	v_rndne_f32_e32 v92, v90
	v_fmac_f32_e32 v91, 0x32a5705f, v89
	v_sub_f32_e32 v90, v90, v92
	v_add_f32_e32 v90, v90, v91
	v_exp_f32_e32 v90, v90
	v_cvt_i32_f32_e32 v91, v92
	v_cmp_ngt_f32_e32 vcc, s6, v89
	v_ldexp_f32 v90, v90, v91
	s_nop 0
	v_cndmask_b32_e32 v90, 0, v90, vcc
	v_cmp_nlt_f32_e32 vcc, s7, v89
	s_nop 1
	v_cndmask_b32_e32 v89, v173, v90, vcc
	v_add_f32_e32 v87, v89, v87
	v_cndmask_b32_e64 v88, v88, v89, s[44:45]
	v_sub_f32_e32 v89, v113, v86
	v_mul_f32_e32 v90, 0x3fb8aa3b, v89
	v_fma_f32 v91, v89, s1, -v90
	v_rndne_f32_e32 v92, v90
	v_fmac_f32_e32 v91, 0x32a5705f, v89
	v_sub_f32_e32 v90, v90, v92
	v_add_f32_e32 v90, v90, v91
	v_exp_f32_e32 v90, v90
	v_cvt_i32_f32_e32 v91, v92
	v_cmp_ngt_f32_e32 vcc, s6, v89
	v_ldexp_f32 v90, v90, v91
	s_nop 0
	v_cndmask_b32_e32 v90, 0, v90, vcc
	v_cmp_nlt_f32_e32 vcc, s7, v89
	s_nop 1
	v_cndmask_b32_e32 v89, v173, v90, vcc
	v_add_f32_e32 v87, v89, v87
	v_cndmask_b32_e64 v88, v88, v89, s[46:47]
	v_sub_f32_e32 v89, v94, v86
	v_mul_f32_e32 v90, 0x3fb8aa3b, v89
	v_fma_f32 v91, v89, s1, -v90
	v_rndne_f32_e32 v92, v90
	v_fmac_f32_e32 v91, 0x32a5705f, v89
	v_sub_f32_e32 v90, v90, v92
	v_add_f32_e32 v90, v90, v91
	v_exp_f32_e32 v90, v90
	v_cvt_i32_f32_e32 v91, v92
	v_cmp_ngt_f32_e32 vcc, s6, v89
	v_ldexp_f32 v90, v90, v91
	s_nop 0
	v_cndmask_b32_e32 v90, 0, v90, vcc
	v_cmp_nlt_f32_e32 vcc, s7, v89
	s_nop 1
	v_cndmask_b32_e32 v89, v173, v90, vcc
	v_add_f32_e32 v87, v89, v87
	v_cndmask_b32_e64 v88, v88, v89, s[48:49]
	v_sub_f32_e32 v89, v95, v86
	v_mul_f32_e32 v90, 0x3fb8aa3b, v89
	v_fma_f32 v91, v89, s1, -v90
	v_rndne_f32_e32 v92, v90
	v_fmac_f32_e32 v91, 0x32a5705f, v89
	v_sub_f32_e32 v90, v90, v92
	v_add_f32_e32 v90, v90, v91
	v_exp_f32_e32 v90, v90
	v_cvt_i32_f32_e32 v91, v92
	v_cmp_ngt_f32_e32 vcc, s6, v89
	v_ldexp_f32 v90, v90, v91
	s_nop 0
	v_cndmask_b32_e32 v90, 0, v90, vcc
	v_cmp_nlt_f32_e32 vcc, s7, v89
	s_nop 1
	v_cndmask_b32_e32 v89, v173, v90, vcc
	v_add_f32_e32 v87, v89, v87
	v_cndmask_b32_e64 v88, v88, v89, s[50:51]
	v_sub_f32_e32 v89, v96, v86
	v_mul_f32_e32 v90, 0x3fb8aa3b, v89
	v_fma_f32 v91, v89, s1, -v90
	v_rndne_f32_e32 v92, v90
	v_fmac_f32_e32 v91, 0x32a5705f, v89
	v_sub_f32_e32 v90, v90, v92
	v_add_f32_e32 v90, v90, v91
	v_exp_f32_e32 v90, v90
	v_cvt_i32_f32_e32 v91, v92
	v_cmp_ngt_f32_e32 vcc, s6, v89
	v_ldexp_f32 v90, v90, v91
	s_nop 0
	v_cndmask_b32_e32 v90, 0, v90, vcc
	v_cmp_nlt_f32_e32 vcc, s7, v89
	s_nop 1
	v_cndmask_b32_e32 v89, v173, v90, vcc
	v_add_f32_e32 v87, v89, v87
	v_cndmask_b32_e64 v88, v88, v89, s[52:53]
	v_sub_f32_e32 v89, v97, v86
	v_mul_f32_e32 v90, 0x3fb8aa3b, v89
	v_fma_f32 v91, v89, s1, -v90
	v_rndne_f32_e32 v92, v90
	v_fmac_f32_e32 v91, 0x32a5705f, v89
	v_sub_f32_e32 v90, v90, v92
	v_add_f32_e32 v90, v90, v91
	v_exp_f32_e32 v90, v90
	v_cvt_i32_f32_e32 v91, v92
	v_cmp_ngt_f32_e32 vcc, s6, v89
	v_ldexp_f32 v90, v90, v91
	s_nop 0
	v_cndmask_b32_e32 v90, 0, v90, vcc
	v_cmp_nlt_f32_e32 vcc, s7, v89
	s_nop 1
	v_cndmask_b32_e32 v89, v173, v90, vcc
	v_add_f32_e32 v87, v89, v87
	v_cndmask_b32_e64 v88, v88, v89, s[54:55]
	v_mul_f32_e32 v89, 0x3fb8aa3b, v82
	v_fma_f32 v90, v82, s1, -v89
	v_rndne_f32_e32 v91, v89
	v_fmac_f32_e32 v90, 0x32a5705f, v82
	v_sub_f32_e32 v89, v89, v91
	v_add_f32_e32 v89, v89, v90
	v_exp_f32_e32 v89, v89
	v_cvt_i32_f32_e32 v90, v91
	v_cmp_ngt_f32_e32 vcc, s6, v82
	v_ldexp_f32 v89, v89, v90
	s_nop 0
	v_cndmask_b32_e32 v89, 0, v89, vcc
	v_cmp_nlt_f32_e32 vcc, s7, v82
	s_nop 1
	v_cndmask_b32_e32 v82, v173, v89, vcc
	v_add_f32_e32 v87, v82, v87
	v_cndmask_b32_e64 v82, v88, v82, s[56:57]
	v_mul_f32_e32 v88, 0x3fb8aa3b, v83
	v_fma_f32 v89, v83, s1, -v88
	v_rndne_f32_e32 v90, v88
	v_fmac_f32_e32 v89, 0x32a5705f, v83
	v_sub_f32_e32 v88, v88, v90
	v_add_f32_e32 v88, v88, v89
	v_exp_f32_e32 v88, v88
	v_cvt_i32_f32_e32 v89, v90
	v_cmp_ngt_f32_e32 vcc, s6, v83
	v_ldexp_f32 v88, v88, v89
	s_nop 0
	v_cndmask_b32_e32 v88, 0, v88, vcc
	v_cmp_nlt_f32_e32 vcc, s7, v83
	s_nop 1
	v_cndmask_b32_e32 v83, v173, v88, vcc
	v_add_f32_e32 v87, v83, v87
	v_cndmask_b32_e64 v82, v82, v83, s[58:59]
	v_sub_f32_e32 v83, v84, v86
	v_mul_f32_e32 v84, 0x3fb8aa3b, v83
	v_fma_f32 v88, v83, s1, -v84
	v_rndne_f32_e32 v89, v84
	v_fmac_f32_e32 v88, 0x32a5705f, v83
	v_sub_f32_e32 v84, v84, v89
	v_add_f32_e32 v84, v84, v88
	v_exp_f32_e32 v84, v84
	v_cvt_i32_f32_e32 v88, v89
	v_cmp_ngt_f32_e32 vcc, s6, v83
	v_ldexp_f32 v84, v84, v88
	s_nop 0
	v_cndmask_b32_e32 v84, 0, v84, vcc
	v_cmp_nlt_f32_e32 vcc, s7, v83
	s_nop 1
	v_cndmask_b32_e32 v83, v173, v84, vcc
	v_add_f32_e32 v84, v83, v87
	v_cndmask_b32_e64 v82, v82, v83, s[60:61]
	v_sub_f32_e32 v83, v85, v86
	v_mul_f32_e32 v85, 0x3fb8aa3b, v83
	v_fma_f32 v86, v83, s1, -v85
	v_rndne_f32_e32 v87, v85
	v_fmac_f32_e32 v86, 0x32a5705f, v83
	v_sub_f32_e32 v85, v85, v87
	v_add_f32_e32 v85, v85, v86
	v_exp_f32_e32 v85, v85
	v_cvt_i32_f32_e32 v86, v87
	v_cmp_ngt_f32_e32 vcc, s6, v83
	v_ldexp_f32 v85, v85, v86
	s_nop 0
	v_cndmask_b32_e32 v85, 0, v85, vcc
	v_cmp_nlt_f32_e32 vcc, s7, v83
	s_nop 1
	v_cndmask_b32_e32 v83, v173, v85, vcc
	v_add_f32_e32 v84, v83, v84
	v_cndmask_b32_e64 v82, v82, v83, s[62:63]
	v_div_scale_f32 v83, s[64:65], v84, v84, v82
	v_rcp_f32_e32 v85, v83
	s_nop 0
	v_fma_f32 v86, -v83, v85, 1.0
	v_fmac_f32_e32 v85, v86, v85
	v_div_scale_f32 v86, vcc, v82, v84, v82
	v_mul_f32_e32 v87, v86, v85
	v_fma_f32 v88, -v83, v87, v86
	v_fmac_f32_e32 v87, v88, v85
	v_fma_f32 v83, -v83, v87, v86
	v_div_fmas_f32 v83, v83, v85, v87
	v_div_fixup_f32 v82, v83, v84, v82
	v_lshl_add_u64 v[84:85], v[154:155], 0, s[86:87]
	v_subrev_co_u32_e32 v84, vcc, 0, v84
	s_add_u32 s86, s86, 0x200
	s_nop 0
	v_subb_co_u32_e32 v85, vcc, v85, v82, vcc
	v_add_u32_e32 v82, s86, v0
	v_add_u32_e32 v82, 0xfffffe01, v82
	s_addc_u32 s87, s87, 0
	v_cmp_lt_u32_e32 vcc, s3, v82
	ds_write_b64 v177, v[84:85]
	ds_write2st64_b32 v134, v167, v179 offset1:32
	v_add_u32_e32 v134, 0x800, v134
	v_add_u32_e32 v177, 0x1000, v177
	s_waitcnt vmcnt(14)
	v_add_f32_e32 v201, v201, v218
	s_waitcnt vmcnt(4)
	v_add_f32_e32 v218, v219, v220
	v_add_f32_e32 v201, v201, v218
	v_fmamk_f32 v201, v201, 0x3a800000, v166
	s_mov_b32 s3, 0xf800000
	v_cmp_gt_f32_e32 vcc, s3, v201
	v_mul_f32_e32 v218, 0x4f800000, v201
	v_add_f32_e32 v46, v46, v202
	v_cndmask_b32_e32 v201, v201, v218, vcc
	v_sqrt_f32_e32 v218, v201
	s_waitcnt vmcnt(3)
	v_add_f32_e32 v202, v206, v210
	v_add_f32_e32 v46, v46, v202
	v_add_f32_e32 v47, v47, v203
	v_add_u32_e32 v219, -1, v218
	v_fma_f32 v220, -v219, v218, v201
	v_cmp_ge_f32_e64 s[64:65], 0, v220
	v_add_u32_e32 v220, 1, v218
	v_add_f32_e32 v202, v207, v211
	v_cndmask_b32_e64 v219, v218, v219, s[64:65]
	v_fma_f32 v218, -v220, v218, v201
	v_cmp_lt_f32_e64 s[64:65], 0, v218
	v_add_f32_e32 v2, v2, v6
	s_waitcnt vmcnt(2)
	v_add_f32_e32 v6, v10, v18
	v_cndmask_b32_e64 v218, v219, v220, s[64:65]
	v_mul_f32_e32 v219, 0x37800000, v218
	v_cndmask_b32_e32 v218, v218, v219, vcc
	v_cmp_class_f32_e32 vcc, v201, v168
	v_add_f32_e32 v47, v47, v202
	v_add_f32_e32 v48, v48, v204
	v_cndmask_b32_e32 v201, v218, v201, vcc
	v_div_scale_f32 v218, s[64:65], v201, v201, 1.0
	v_rcp_f32_e32 v219, v218
	v_add_f32_e32 v202, v208, v212
	v_add_f32_e32 v30, v30, v38
	s_waitcnt vmcnt(0)
	v_add_f32_e32 v38, v42, v214
	v_fma_f32 v220, -v218, v219, 1.0
	v_fmac_f32_e32 v219, v220, v219
	v_div_scale_f32 v220, vcc, 1.0, v201, 1.0
	v_mul_f32_e32 v221, v220, v219
	v_fma_f32 v222, -v218, v221, v220
	v_fmac_f32_e32 v221, v222, v219
	v_fma_f32 v218, -v218, v221, v220
	v_div_fmas_f32 v218, v218, v219, v221
	v_add_f32_e32 v2, v2, v6
	v_add_f32_e32 v3, v3, v7
	v_add_f32_e32 v6, v11, v19
	v_div_fixup_f32 v201, v218, v201, 1.0
	v_add_f32_e32 v48, v48, v202
	v_add_f32_e32 v49, v49, v205
	v_add_f32_e32 v202, v209, v213
	v_add_f32_e32 v30, v30, v38
	v_add_f32_e32 v31, v31, v39
	v_add_f32_e32 v38, v43, v215
	v_add_f32_e32 v3, v3, v6
	v_add_f32_e32 v4, v4, v8
	v_add_f32_e32 v6, v12, v20
	v_fma_f32 v46, v46, v201, v66
	v_fma_f32 v47, v47, v201, v67
	v_add_f32_e32 v49, v49, v202
	v_add_f32_e32 v31, v31, v38
	v_add_f32_e32 v32, v32, v40
	v_add_f32_e32 v38, v44, v216
	v_add_f32_e32 v14, v14, v22
	v_add_f32_e32 v22, v26, v34
	v_add_f32_e32 v4, v4, v6
	v_add_f32_e32 v5, v5, v9
	v_add_f32_e32 v6, v13, v21
	v_fma_f32 v48, v48, v201, v68
	v_fma_f32 v49, v49, v201, v69
	v_add_f32_e32 v32, v32, v38
	v_add_f32_e32 v33, v33, v41
	v_add_f32_e32 v38, v45, v217
	v_add_f32_e32 v14, v14, v22
	v_add_f32_e32 v15, v15, v23
	v_add_f32_e32 v22, v27, v35
	v_add_f32_e32 v5, v5, v6
	v_max_f32_e32 v6, v46, v47
	v_fma_f32 v30, v30, v201, v70
	v_fma_f32 v31, v31, v201, v71
	v_add_f32_e32 v33, v33, v38
	v_add_f32_e32 v15, v15, v22
	v_add_f32_e32 v16, v16, v24
	v_add_f32_e32 v22, v28, v36
	v_max3_f32 v6, v6, v48, v49
	v_fma_f32 v32, v32, v201, v72
	v_fma_f32 v33, v33, v201, v73
	v_add_f32_e32 v16, v16, v22
	v_add_f32_e32 v17, v17, v25
	v_add_f32_e32 v22, v29, v37
	v_max3_f32 v6, v6, v30, v31
	v_fma_f32 v14, v201, v14, v74
	v_fma_f32 v15, v201, v15, v75
	v_add_f32_e32 v17, v17, v22
	v_max3_f32 v6, v6, v32, v33
	v_fma_f32 v16, v201, v16, v76
	v_fma_f32 v17, v201, v17, v77
	v_max3_f32 v6, v6, v14, v15
	v_fma_f32 v2, v201, v2, v78
	v_fma_f32 v3, v201, v3, v79
	v_max3_f32 v6, v6, v16, v17
	v_fma_f32 v4, v201, v4, v80
	v_fma_f32 v5, v201, v5, v81
	v_max3_f32 v6, v6, v2, v3
	v_max3_f32 v6, v6, v4, v5
	v_sub_f32_e32 v7, v46, v6
	v_mul_f32_e32 v8, 0x3fb8aa3b, v7
	v_fma_f32 v9, v7, s1, -v8
	v_rndne_f32_e32 v10, v8
	v_fmac_f32_e32 v9, 0x32a5705f, v7
	v_sub_f32_e32 v8, v8, v10
	v_add_f32_e32 v8, v8, v9
	v_exp_f32_e32 v8, v8
	v_cvt_i32_f32_e32 v9, v10
	v_cmp_ngt_f32_e32 vcc, s6, v7
	v_sub_f32_e32 v2, v2, v6
	v_sub_f32_e32 v3, v3, v6
	v_ldexp_f32 v8, v8, v9
	v_sub_f32_e32 v9, v47, v6
	v_mul_f32_e32 v10, 0x3fb8aa3b, v9
	v_fma_f32 v11, v9, s1, -v10
	v_rndne_f32_e32 v12, v10
	v_fmac_f32_e32 v11, 0x32a5705f, v9
	v_sub_f32_e32 v10, v10, v12
	v_add_f32_e32 v10, v10, v11
	v_exp_f32_e32 v10, v10
	v_cvt_i32_f32_e32 v11, v12
	v_cndmask_b32_e32 v8, 0, v8, vcc
	v_cmp_nlt_f32_e32 vcc, s7, v7
	s_movk_i32 s3, 0x5ff
	v_ldexp_f32 v10, v10, v11
	v_cndmask_b32_e32 v7, v173, v8, vcc
	v_cmp_ngt_f32_e32 vcc, s6, v9
	v_cndmask_b32_e64 v8, 0, v7, s[30:31]
	v_cndmask_b32_e32 v10, 0, v10, vcc
	v_cmp_nlt_f32_e32 vcc, s7, v9
	s_nop 0
	v_cndmask_b32_e32 v9, v173, v10, vcc
	v_add_f32_e32 v7, v7, v9
	v_cndmask_b32_e64 v8, v8, v9, s[34:35]
	v_sub_f32_e32 v9, v48, v6
	v_mul_f32_e32 v10, 0x3fb8aa3b, v9
	v_fma_f32 v11, v9, s1, -v10
	v_rndne_f32_e32 v12, v10
	v_fmac_f32_e32 v11, 0x32a5705f, v9
	v_sub_f32_e32 v10, v10, v12
	v_add_f32_e32 v10, v10, v11
	v_exp_f32_e32 v10, v10
	v_cvt_i32_f32_e32 v11, v12
	v_cmp_ngt_f32_e32 vcc, s6, v9
	v_ldexp_f32 v10, v10, v11
	s_nop 0
	v_cndmask_b32_e32 v10, 0, v10, vcc
	v_cmp_nlt_f32_e32 vcc, s7, v9
	s_nop 1
	v_cndmask_b32_e32 v9, v173, v10, vcc
	v_add_f32_e32 v7, v9, v7
	v_cndmask_b32_e64 v8, v8, v9, s[36:37]
	v_sub_f32_e32 v9, v49, v6
	v_mul_f32_e32 v10, 0x3fb8aa3b, v9
	v_fma_f32 v11, v9, s1, -v10
	v_rndne_f32_e32 v12, v10
	v_fmac_f32_e32 v11, 0x32a5705f, v9
	v_sub_f32_e32 v10, v10, v12
	v_add_f32_e32 v10, v10, v11
	v_exp_f32_e32 v10, v10
	v_cvt_i32_f32_e32 v11, v12
	v_cmp_ngt_f32_e32 vcc, s6, v9
	v_ldexp_f32 v10, v10, v11
	s_nop 0
	v_cndmask_b32_e32 v10, 0, v10, vcc
	v_cmp_nlt_f32_e32 vcc, s7, v9
	s_nop 1
	v_cndmask_b32_e32 v9, v173, v10, vcc
	v_add_f32_e32 v7, v9, v7
	v_cndmask_b32_e64 v8, v8, v9, s[38:39]
	v_sub_f32_e32 v9, v30, v6
	v_mul_f32_e32 v10, 0x3fb8aa3b, v9
	v_fma_f32 v11, v9, s1, -v10
	v_rndne_f32_e32 v12, v10
	v_fmac_f32_e32 v11, 0x32a5705f, v9
	v_sub_f32_e32 v10, v10, v12
	v_add_f32_e32 v10, v10, v11
	v_exp_f32_e32 v10, v10
	v_cvt_i32_f32_e32 v11, v12
	v_cmp_ngt_f32_e32 vcc, s6, v9
	v_ldexp_f32 v10, v10, v11
	s_nop 0
	v_cndmask_b32_e32 v10, 0, v10, vcc
	v_cmp_nlt_f32_e32 vcc, s7, v9
	s_nop 1
	v_cndmask_b32_e32 v9, v173, v10, vcc
	v_add_f32_e32 v7, v9, v7
	v_cndmask_b32_e64 v8, v8, v9, s[40:41]
	v_sub_f32_e32 v9, v31, v6
	v_mul_f32_e32 v10, 0x3fb8aa3b, v9
	v_fma_f32 v11, v9, s1, -v10
	v_rndne_f32_e32 v12, v10
	v_fmac_f32_e32 v11, 0x32a5705f, v9
	v_sub_f32_e32 v10, v10, v12
	v_add_f32_e32 v10, v10, v11
	v_exp_f32_e32 v10, v10
	v_cvt_i32_f32_e32 v11, v12
	v_cmp_ngt_f32_e32 vcc, s6, v9
	v_ldexp_f32 v10, v10, v11
	s_nop 0
	v_cndmask_b32_e32 v10, 0, v10, vcc
	v_cmp_nlt_f32_e32 vcc, s7, v9
	s_nop 1
	v_cndmask_b32_e32 v9, v173, v10, vcc
	v_add_f32_e32 v7, v9, v7
	v_cndmask_b32_e64 v8, v8, v9, s[42:43]
	v_sub_f32_e32 v9, v32, v6
	v_mul_f32_e32 v10, 0x3fb8aa3b, v9
	v_fma_f32 v11, v9, s1, -v10
	v_rndne_f32_e32 v12, v10
	v_fmac_f32_e32 v11, 0x32a5705f, v9
	v_sub_f32_e32 v10, v10, v12
	v_add_f32_e32 v10, v10, v11
	v_exp_f32_e32 v10, v10
	v_cvt_i32_f32_e32 v11, v12
	v_cmp_ngt_f32_e32 vcc, s6, v9
	v_ldexp_f32 v10, v10, v11
	s_nop 0
	v_cndmask_b32_e32 v10, 0, v10, vcc
	v_cmp_nlt_f32_e32 vcc, s7, v9
	s_nop 1
	v_cndmask_b32_e32 v9, v173, v10, vcc
	v_add_f32_e32 v7, v9, v7
	v_cndmask_b32_e64 v8, v8, v9, s[44:45]
	v_sub_f32_e32 v9, v33, v6
	v_mul_f32_e32 v10, 0x3fb8aa3b, v9
	v_fma_f32 v11, v9, s1, -v10
	v_rndne_f32_e32 v12, v10
	v_fmac_f32_e32 v11, 0x32a5705f, v9
	v_sub_f32_e32 v10, v10, v12
	v_add_f32_e32 v10, v10, v11
	v_exp_f32_e32 v10, v10
	v_cvt_i32_f32_e32 v11, v12
	v_cmp_ngt_f32_e32 vcc, s6, v9
	v_ldexp_f32 v10, v10, v11
	s_nop 0
	v_cndmask_b32_e32 v10, 0, v10, vcc
	v_cmp_nlt_f32_e32 vcc, s7, v9
	s_nop 1
	v_cndmask_b32_e32 v9, v173, v10, vcc
	v_add_f32_e32 v7, v9, v7
	v_cndmask_b32_e64 v8, v8, v9, s[46:47]
	v_sub_f32_e32 v9, v14, v6
	v_mul_f32_e32 v10, 0x3fb8aa3b, v9
	v_fma_f32 v11, v9, s1, -v10
	v_rndne_f32_e32 v12, v10
	v_fmac_f32_e32 v11, 0x32a5705f, v9
	v_sub_f32_e32 v10, v10, v12
	v_add_f32_e32 v10, v10, v11
	v_exp_f32_e32 v10, v10
	v_cvt_i32_f32_e32 v11, v12
	v_cmp_ngt_f32_e32 vcc, s6, v9
	v_ldexp_f32 v10, v10, v11
	s_nop 0
	v_cndmask_b32_e32 v10, 0, v10, vcc
	v_cmp_nlt_f32_e32 vcc, s7, v9
	s_nop 1
	v_cndmask_b32_e32 v9, v173, v10, vcc
	v_add_f32_e32 v7, v9, v7
	v_cndmask_b32_e64 v8, v8, v9, s[48:49]
	v_sub_f32_e32 v9, v15, v6
	v_mul_f32_e32 v10, 0x3fb8aa3b, v9
	v_fma_f32 v11, v9, s1, -v10
	v_rndne_f32_e32 v12, v10
	v_fmac_f32_e32 v11, 0x32a5705f, v9
	v_sub_f32_e32 v10, v10, v12
	v_add_f32_e32 v10, v10, v11
	v_exp_f32_e32 v10, v10
	v_cvt_i32_f32_e32 v11, v12
	v_cmp_ngt_f32_e32 vcc, s6, v9
	v_ldexp_f32 v10, v10, v11
	s_nop 0
	v_cndmask_b32_e32 v10, 0, v10, vcc
	v_cmp_nlt_f32_e32 vcc, s7, v9
	s_nop 1
	v_cndmask_b32_e32 v9, v173, v10, vcc
	v_add_f32_e32 v7, v9, v7
	v_cndmask_b32_e64 v8, v8, v9, s[50:51]
	v_sub_f32_e32 v9, v16, v6
	v_mul_f32_e32 v10, 0x3fb8aa3b, v9
	v_fma_f32 v11, v9, s1, -v10
	v_rndne_f32_e32 v12, v10
	v_fmac_f32_e32 v11, 0x32a5705f, v9
	v_sub_f32_e32 v10, v10, v12
	v_add_f32_e32 v10, v10, v11
	v_exp_f32_e32 v10, v10
	v_cvt_i32_f32_e32 v11, v12
	v_cmp_ngt_f32_e32 vcc, s6, v9
	v_ldexp_f32 v10, v10, v11
	s_nop 0
	v_cndmask_b32_e32 v10, 0, v10, vcc
	v_cmp_nlt_f32_e32 vcc, s7, v9
	s_nop 1
	v_cndmask_b32_e32 v9, v173, v10, vcc
	v_add_f32_e32 v7, v9, v7
	v_cndmask_b32_e64 v8, v8, v9, s[52:53]
	v_sub_f32_e32 v9, v17, v6
	v_mul_f32_e32 v10, 0x3fb8aa3b, v9
	v_fma_f32 v11, v9, s1, -v10
	v_rndne_f32_e32 v12, v10
	v_fmac_f32_e32 v11, 0x32a5705f, v9
	v_sub_f32_e32 v10, v10, v12
	v_add_f32_e32 v10, v10, v11
	v_exp_f32_e32 v10, v10
	v_cvt_i32_f32_e32 v11, v12
	v_cmp_ngt_f32_e32 vcc, s6, v9
	v_ldexp_f32 v10, v10, v11
	s_nop 0
	v_cndmask_b32_e32 v10, 0, v10, vcc
	v_cmp_nlt_f32_e32 vcc, s7, v9
	s_nop 1
	v_cndmask_b32_e32 v9, v173, v10, vcc
	v_add_f32_e32 v7, v9, v7
	v_cndmask_b32_e64 v8, v8, v9, s[54:55]
	v_mul_f32_e32 v9, 0x3fb8aa3b, v2
	v_fma_f32 v10, v2, s1, -v9
	v_rndne_f32_e32 v11, v9
	v_fmac_f32_e32 v10, 0x32a5705f, v2
	v_sub_f32_e32 v9, v9, v11
	v_add_f32_e32 v9, v9, v10
	v_exp_f32_e32 v9, v9
	v_cvt_i32_f32_e32 v10, v11
	v_cmp_ngt_f32_e32 vcc, s6, v2
	v_ldexp_f32 v9, v9, v10
	s_nop 0
	v_cndmask_b32_e32 v9, 0, v9, vcc
	v_cmp_nlt_f32_e32 vcc, s7, v2
	s_nop 1
	v_cndmask_b32_e32 v2, v173, v9, vcc
	v_add_f32_e32 v7, v2, v7
	v_cndmask_b32_e64 v2, v8, v2, s[56:57]
	v_mul_f32_e32 v8, 0x3fb8aa3b, v3
	v_fma_f32 v9, v3, s1, -v8
	v_rndne_f32_e32 v10, v8
	v_fmac_f32_e32 v9, 0x32a5705f, v3
	v_sub_f32_e32 v8, v8, v10
	v_add_f32_e32 v8, v8, v9
	v_exp_f32_e32 v8, v8
	v_cvt_i32_f32_e32 v9, v10
	v_cmp_ngt_f32_e32 vcc, s6, v3
	v_ldexp_f32 v8, v8, v9
	s_nop 0
	v_cndmask_b32_e32 v8, 0, v8, vcc
	v_cmp_nlt_f32_e32 vcc, s7, v3
	s_nop 1
	v_cndmask_b32_e32 v3, v173, v8, vcc
	v_add_f32_e32 v7, v3, v7
	v_cndmask_b32_e64 v2, v2, v3, s[58:59]
	v_sub_f32_e32 v3, v4, v6
	v_mul_f32_e32 v4, 0x3fb8aa3b, v3
	v_fma_f32 v8, v3, s1, -v4
	v_rndne_f32_e32 v9, v4
	v_fmac_f32_e32 v8, 0x32a5705f, v3
	v_sub_f32_e32 v4, v4, v9
	v_add_f32_e32 v4, v4, v8
	v_exp_f32_e32 v4, v4
	v_cvt_i32_f32_e32 v8, v9
	v_cmp_ngt_f32_e32 vcc, s6, v3
	v_ldexp_f32 v4, v4, v8
	s_nop 0
	v_cndmask_b32_e32 v4, 0, v4, vcc
	v_cmp_nlt_f32_e32 vcc, s7, v3
	s_nop 1
	v_cndmask_b32_e32 v3, v173, v4, vcc
	v_add_f32_e32 v4, v3, v7
	v_cndmask_b32_e64 v2, v2, v3, s[60:61]
	v_sub_f32_e32 v3, v5, v6
	v_mul_f32_e32 v5, 0x3fb8aa3b, v3
	v_fma_f32 v6, v3, s1, -v5
	v_rndne_f32_e32 v7, v5
	v_fmac_f32_e32 v6, 0x32a5705f, v3
	v_sub_f32_e32 v5, v5, v7
	v_add_f32_e32 v5, v5, v6
	v_exp_f32_e32 v5, v5
	v_cvt_i32_f32_e32 v6, v7
	v_cmp_ngt_f32_e32 vcc, s6, v3
	v_ldexp_f32 v5, v5, v6
	s_nop 0
	v_cndmask_b32_e32 v5, 0, v5, vcc
	v_cmp_nlt_f32_e32 vcc, s7, v3
	s_nop 1
	v_cndmask_b32_e32 v3, v173, v5, vcc
	v_add_f32_e32 v4, v3, v4
	v_cndmask_b32_e64 v2, v2, v3, s[62:63]
	v_div_scale_f32 v3, s[64:65], v4, v4, v2
	v_rcp_f32_e32 v5, v3
	s_nop 0
	v_fma_f32 v6, -v3, v5, 1.0
	v_fmac_f32_e32 v5, v6, v5
	v_div_scale_f32 v6, vcc, v2, v4, v2
	v_mul_f32_e32 v7, v6, v5
	v_fma_f32 v8, -v3, v7, v6
	v_fmac_f32_e32 v7, v8, v5
	v_fma_f32 v3, -v3, v7, v6
	v_div_fmas_f32 v3, v3, v5, v7
	v_div_fixup_f32 v2, v3, v4, v2
	v_lshl_add_u64 v[4:5], v[154:155], 0, s[86:87]
	v_subrev_co_u32_e32 v4, vcc, 0, v4
	s_add_u32 s86, s86, 0x200
	s_nop 0
	v_subb_co_u32_e32 v5, vcc, v5, v2, vcc
	v_add_u32_e32 v2, s86, v0
	v_add_u32_e32 v2, 0xfffffe01, v2
	s_addc_u32 s87, s87, 0
	v_cmp_lt_u32_e32 vcc, s3, v2
	ds_write_b64 v177, v[4:5]
	ds_write2st64_b32 v134, v167, v201 offset1:32
	v_add_u32_e32 v134, 0x800, v134
	v_add_u32_e32 v177, 0x1000, v177
	s_or_b64 exec, exec, s[66:67]
	s_and_b64 vcc, exec, s[28:29]
	s_waitcnt lgkmcnt(0)
	s_barrier
	s_cbranch_vccz .LBB0_1407
	v_readlane_b32 s36, v252, 42
	s_cmpk_gt_u32 s85, 0xcc7f
	v_readlane_b32 s37, v252, 43
	v_readlane_b32 s38, v252, 44
	v_readlane_b32 s39, v252, 45
	v_readlane_b32 s42, v252, 48
	v_readlane_b32 s43, v252, 49
	v_readlane_b32 s44, v252, 50
	v_readlane_b32 s45, v252, 51
	v_readlane_b32 s46, v252, 52
	v_readlane_b32 s47, v252, 53
	v_readlane_b32 s40, v252, 46
	v_readlane_b32 s41, v252, 47
	v_readlane_b32 s48, v252, 54
	v_readlane_b32 s49, v252, 55
	v_readlane_b32 s50, v252, 56
	v_readlane_b32 s51, v252, 57
	s_cbranch_scc1 .LBB0_1424
	s_cmpk_gt_u32 s85, 0x87f
	s_mov_b64 s[30:31], -1
	v_writelane_b32 v252, s34, 58
	s_nop 1
	v_writelane_b32 v252, s35, 59
	s_cbranch_scc0 .LBB0_1420
	s_cmpk_gt_u32 s85, 0x97f
	s_cbranch_scc0 .LBB0_1408
	s_cmpk_gt_u32 s85, 0xa7f
	s_cbranch_scc0 .LBB0_1409
	s_cmpk_gt_u32 s85, 0xc7f
	s_cbranch_scc0 .LBB0_1410
	s_add_i32 s2, s85, 0xfffff380
	s_mul_i32 s3, s2, 0xaaab
	s_lshr_b32 s5, s3, 27
	s_mul_i32 s13, s5, 0xfffff400
	s_add_i32 s13, s13, s2
	s_cmpk_gt_i32 s13, 0x7ff
	s_mov_b64 s[2:3], -1
	s_cbranch_scc0 .LBB0_1405
	s_lshl_b32 s2, s5, 23
	s_add_u32 s2, s46, s2
	s_addc_u32 s3, s47, 0
	v_writelane_b32 v251, s2, 57
	s_nop 1
	v_writelane_b32 v251, s3, 58
	s_lshl_b32 s2, s13, 1
	s_and_b32 s2, s2, 0x7fffffc0
	s_add_i32 s26, s2, 0xfffff000
	s_lshl_b32 s2, s85, 5
	s_and_b32 s30, s2, 0x3e0
	s_lshl_b32 s2, s5, 10
	s_or_b32 s2, s2, s30
	v_writelane_b32 v251, s2, 56
	s_mov_b64 s[2:3], 0
